# GEMM K-loops: LDS-DMA loads use SGPR base + 32-bit lane offset (16 address VALU per iteration removed from the load segments)
# speedup vs baseline: 1.0046x; 1.0001x over previous
.LBB0_201:
	s_add_u32 s12, s54, 0xfff00080
	s_addc_u32 s13, s55, -1
	s_add_i32 s16, 0, 0x10000
	s_cmp_eq_u32 s66, 60
	s_cselect_b32 s57, s43, s13
	s_cselect_b32 s56, s60, s12
	s_cselect_b32 s13, s37, s63
	s_cselect_b32 s12, s61, s62
	s_add_i32 s17, 0, 0x14000
	v_add_u32_e32 v158, s16, v115
	v_add_u32_e32 v174, s17, v115
	ds_read_b128 v[144:147], v158
	ds_read_b128 v[148:151], v158 offset:1024
	ds_read_b128 v[154:157], v158 offset:2048
	ds_read_b128 v[158:161], v158 offset:3072
	ds_read_b128 v[162:165], v174
	ds_read_b128 v[166:169], v174 offset:1024
	ds_read_b128 v[170:173], v174 offset:2048
	ds_read_b128 v[174:177], v174 offset:3072
	s_add_i32 m0, s23, 0xc000
	ds_read_b128 v[194:197], v153
	ds_read_b128 v[198:201], v153 offset:1024
	ds_read_b128 v[214:217], v153 offset:2048
	ds_read_b128 v[218:221], v153 offset:3072
	ds_read_b128 v[222:225], v153 offset:4096
	ds_read_b128 v[226:229], v153 offset:5120
	ds_read_b128 v[230:233], v153 offset:6144
	ds_read_b128 v[234:237], v153 offset:7168
	global_load_lds_dwordx4 v140, s[54:55]
	s_add_i32 m0, s23, 0xe000
	s_nop 0
	global_load_lds_dwordx4 v142, s[54:55]
	s_waitcnt vmcnt(8)
	s_waitcnt lgkmcnt(0)
	s_barrier
	s_setprio 1
	s_waitcnt lgkmcnt(0)
	v_mfma_f32_16x16x32_bf16 v[128:131], v[144:147], v[194:197], v[128:131]
	v_mfma_f32_16x16x32_bf16 v[124:127], v[154:157], v[194:197], v[124:127]
	v_mfma_f32_16x16x32_bf16 v[110:113], v[144:147], v[214:217], v[110:113]
	v_mfma_f32_16x16x32_bf16 v[106:109], v[154:157], v[214:217], v[106:109]
	v_mfma_f32_16x16x32_bf16 v[94:97], v[144:147], v[222:225], v[94:97]
	v_mfma_f32_16x16x32_bf16 v[90:93], v[154:157], v[222:225], v[90:93]
	v_mfma_f32_16x16x32_bf16 v[78:81], v[144:147], v[230:233], v[78:81]
	v_mfma_f32_16x16x32_bf16 v[74:77], v[154:157], v[230:233], v[74:77]
	v_mfma_f32_16x16x32_bf16 v[128:131], v[148:151], v[198:201], v[128:131]
	v_mfma_f32_16x16x32_bf16 v[124:127], v[158:161], v[198:201], v[124:127]
	v_mfma_f32_16x16x32_bf16 v[110:113], v[148:151], v[218:221], v[110:113]
	v_mfma_f32_16x16x32_bf16 v[106:109], v[158:161], v[218:221], v[106:109]
	v_mfma_f32_16x16x32_bf16 v[94:97], v[148:151], v[226:229], v[94:97]
	v_mfma_f32_16x16x32_bf16 v[90:93], v[158:161], v[226:229], v[90:93]
	v_mfma_f32_16x16x32_bf16 v[78:81], v[148:151], v[234:237], v[78:81]
	v_mfma_f32_16x16x32_bf16 v[74:77], v[158:161], v[234:237], v[74:77]
	s_setprio 0
	s_setprio 1
	v_mfma_f32_16x16x32_bf16 v[120:123], v[162:165], v[194:197], v[120:123]
	v_mfma_f32_16x16x32_bf16 v[116:119], v[170:173], v[194:197], v[116:119]
	v_mfma_f32_16x16x32_bf16 v[102:105], v[162:165], v[214:217], v[102:105]
	v_mfma_f32_16x16x32_bf16 v[98:101], v[170:173], v[214:217], v[98:101]
	v_mfma_f32_16x16x32_bf16 v[86:89], v[162:165], v[222:225], v[86:89]
	v_mfma_f32_16x16x32_bf16 v[82:85], v[170:173], v[222:225], v[82:85]
	v_mfma_f32_16x16x32_bf16 v[70:73], v[162:165], v[230:233], v[70:73]
	v_mfma_f32_16x16x32_bf16 v[66:69], v[170:173], v[230:233], v[66:69]
	v_mfma_f32_16x16x32_bf16 v[120:123], v[166:169], v[198:201], v[120:123]
	v_mfma_f32_16x16x32_bf16 v[116:119], v[174:177], v[198:201], v[116:119]
	v_mfma_f32_16x16x32_bf16 v[102:105], v[166:169], v[218:221], v[102:105]
	v_mfma_f32_16x16x32_bf16 v[98:101], v[174:177], v[218:221], v[98:101]
	v_mfma_f32_16x16x32_bf16 v[86:89], v[166:169], v[226:229], v[86:89]
	v_mfma_f32_16x16x32_bf16 v[82:85], v[174:177], v[226:229], v[82:85]
	v_mfma_f32_16x16x32_bf16 v[70:73], v[166:169], v[234:237], v[70:73]
	v_mfma_f32_16x16x32_bf16 v[66:69], v[174:177], v[234:237], v[66:69]
	s_setprio 0
	s_barrier
	s_add_i32 s16, s16, s26
	s_mov_b32 m0, s16
	ds_read_b128 v[194:197], v153 offset:16384
	ds_read_b128 v[198:201], v153 offset:17408
	ds_read_b128 v[214:217], v153 offset:18432
	ds_read_b128 v[218:221], v153 offset:19456
	ds_read_b128 v[222:225], v153 offset:20480
	ds_read_b128 v[226:229], v153 offset:21504
	ds_read_b128 v[230:233], v153 offset:22528
	ds_read_b128 v[234:237], v153 offset:23552
	global_load_lds_dwordx4 v136, s[12:13]
	s_add_i32 m0, s16, 0x2000
	s_add_u32 s68, s12, 0x4000
	s_addc_u32 s69, s13, 0
	s_add_i32 s16, s17, s26
	global_load_lds_dwordx4 v132, s[12:13]
	s_mov_b32 m0, s16
	s_nop 0
	global_load_lds_dwordx4 v136, s[68:69]
	s_add_i32 m0, s16, 0x2000
	s_nop 0
	global_load_lds_dwordx4 v132, s[68:69]
	s_add_u32 vcc_lo, s56, s64
	s_addc_u32 vcc_hi, s57, s65
	s_mov_b32 m0, s23
	s_nop 0
	global_load_lds_dwordx4 v138, s[56:57]
	s_mov_b32 m0, s24
	s_nop 0
	global_load_lds_dwordx4 v134, s[56:57]
	s_waitcnt vmcnt(8)
	s_waitcnt lgkmcnt(0)
	s_barrier
	s_setprio 1
	s_waitcnt lgkmcnt(0)
	v_mfma_f32_16x16x32_bf16 v[62:65], v[144:147], v[194:197], v[62:65]
	v_mfma_f32_16x16x32_bf16 v[58:61], v[154:157], v[194:197], v[58:61]
	v_mfma_f32_16x16x32_bf16 v[46:49], v[144:147], v[214:217], v[46:49]
	v_mfma_f32_16x16x32_bf16 v[42:45], v[154:157], v[214:217], v[42:45]
	v_mfma_f32_16x16x32_bf16 v[30:33], v[144:147], v[222:225], v[30:33]
	v_mfma_f32_16x16x32_bf16 v[26:29], v[154:157], v[222:225], v[26:29]
	v_mfma_f32_16x16x32_bf16 v[14:17], v[144:147], v[230:233], v[14:17]
	v_mfma_f32_16x16x32_bf16 v[10:13], v[154:157], v[230:233], v[10:13]
	v_mfma_f32_16x16x32_bf16 v[62:65], v[148:151], v[198:201], v[62:65]
	v_mfma_f32_16x16x32_bf16 v[58:61], v[158:161], v[198:201], v[58:61]
	v_mfma_f32_16x16x32_bf16 v[46:49], v[148:151], v[218:221], v[46:49]
	v_mfma_f32_16x16x32_bf16 v[42:45], v[158:161], v[218:221], v[42:45]
	v_mfma_f32_16x16x32_bf16 v[30:33], v[148:151], v[226:229], v[30:33]
	v_mfma_f32_16x16x32_bf16 v[26:29], v[158:161], v[226:229], v[26:29]
	v_mfma_f32_16x16x32_bf16 v[14:17], v[148:151], v[234:237], v[14:17]
	v_mfma_f32_16x16x32_bf16 v[10:13], v[158:161], v[234:237], v[10:13]
	s_setprio 0
	s_setprio 1
	v_mfma_f32_16x16x32_bf16 v[54:57], v[162:165], v[194:197], v[54:57]
	v_mfma_f32_16x16x32_bf16 v[50:53], v[170:173], v[194:197], v[50:53]
	v_mfma_f32_16x16x32_bf16 v[38:41], v[162:165], v[214:217], v[38:41]
	v_mfma_f32_16x16x32_bf16 v[34:37], v[170:173], v[214:217], v[34:37]
	v_mfma_f32_16x16x32_bf16 v[22:25], v[162:165], v[222:225], v[22:25]
	v_mfma_f32_16x16x32_bf16 v[18:21], v[170:173], v[222:225], v[18:21]
	v_mfma_f32_16x16x32_bf16 v[6:9], v[162:165], v[230:233], v[6:9]
	v_mfma_f32_16x16x32_bf16 v[2:5], v[170:173], v[230:233], v[2:5]
	v_mfma_f32_16x16x32_bf16 v[54:57], v[166:169], v[198:201], v[54:57]
	v_mfma_f32_16x16x32_bf16 v[50:53], v[174:177], v[198:201], v[50:53]
	v_mfma_f32_16x16x32_bf16 v[38:41], v[166:169], v[218:221], v[38:41]
	v_mfma_f32_16x16x32_bf16 v[34:37], v[174:177], v[218:221], v[34:37]
	v_mfma_f32_16x16x32_bf16 v[22:25], v[166:169], v[226:229], v[22:25]
	v_mfma_f32_16x16x32_bf16 v[18:21], v[174:177], v[226:229], v[18:21]
	v_mfma_f32_16x16x32_bf16 v[6:9], v[166:169], v[234:237], v[6:9]
	v_mfma_f32_16x16x32_bf16 v[2:5], v[174:177], v[234:237], v[2:5]
	s_setprio 0
	s_barrier
	s_add_i32 s16, 0, 0x18000
	s_add_i32 s17, 0, 0x1c000
	v_add_u32_e32 v158, s16, v115
	v_add_u32_e32 v174, s17, v115
	ds_read_b128 v[144:147], v158
	ds_read_b128 v[148:151], v158 offset:1024
	ds_read_b128 v[154:157], v158 offset:2048
	ds_read_b128 v[158:161], v158 offset:3072
	ds_read_b128 v[162:165], v174
	ds_read_b128 v[166:169], v174 offset:1024
	ds_read_b128 v[170:173], v174 offset:2048
	ds_read_b128 v[174:177], v174 offset:3072
	s_add_u32 s56, s56, 0x100000
	s_addc_u32 s57, s57, 0
	s_mov_b32 m0, s27
	ds_read_b128 v[194:197], v153 offset:32768
	ds_read_b128 v[198:201], v153 offset:33792
	ds_read_b128 v[214:217], v153 offset:34816
	ds_read_b128 v[218:221], v153 offset:35840
	ds_read_b128 v[222:225], v153 offset:36864
	ds_read_b128 v[226:229], v153 offset:37888
	ds_read_b128 v[230:233], v153 offset:38912
	ds_read_b128 v[234:237], v153 offset:39936
	global_load_lds_dwordx4 v138, s[56:57]
	s_mov_b32 m0, s28
	s_nop 0
	global_load_lds_dwordx4 v134, s[56:57]
	s_waitcnt vmcnt(8)
	s_waitcnt lgkmcnt(0)
	s_barrier
	s_setprio 1
	s_waitcnt lgkmcnt(0)
	v_mfma_f32_16x16x32_bf16 v[128:131], v[144:147], v[194:197], v[128:131]
	v_mfma_f32_16x16x32_bf16 v[124:127], v[154:157], v[194:197], v[124:127]
	v_mfma_f32_16x16x32_bf16 v[110:113], v[144:147], v[214:217], v[110:113]
	v_mfma_f32_16x16x32_bf16 v[106:109], v[154:157], v[214:217], v[106:109]
	v_mfma_f32_16x16x32_bf16 v[94:97], v[144:147], v[222:225], v[94:97]
	v_mfma_f32_16x16x32_bf16 v[90:93], v[154:157], v[222:225], v[90:93]
	v_mfma_f32_16x16x32_bf16 v[78:81], v[144:147], v[230:233], v[78:81]
	v_mfma_f32_16x16x32_bf16 v[74:77], v[154:157], v[230:233], v[74:77]
	v_mfma_f32_16x16x32_bf16 v[128:131], v[148:151], v[198:201], v[128:131]
	v_mfma_f32_16x16x32_bf16 v[124:127], v[158:161], v[198:201], v[124:127]
	v_mfma_f32_16x16x32_bf16 v[110:113], v[148:151], v[218:221], v[110:113]
	v_mfma_f32_16x16x32_bf16 v[106:109], v[158:161], v[218:221], v[106:109]
	v_mfma_f32_16x16x32_bf16 v[94:97], v[148:151], v[226:229], v[94:97]
	v_mfma_f32_16x16x32_bf16 v[90:93], v[158:161], v[226:229], v[90:93]
	v_mfma_f32_16x16x32_bf16 v[78:81], v[148:151], v[234:237], v[78:81]
	v_mfma_f32_16x16x32_bf16 v[74:77], v[158:161], v[234:237], v[74:77]
	s_setprio 0
	s_setprio 1
	v_mfma_f32_16x16x32_bf16 v[120:123], v[162:165], v[194:197], v[120:123]
	v_mfma_f32_16x16x32_bf16 v[116:119], v[170:173], v[194:197], v[116:119]
	v_mfma_f32_16x16x32_bf16 v[102:105], v[162:165], v[214:217], v[102:105]
	v_mfma_f32_16x16x32_bf16 v[98:101], v[170:173], v[214:217], v[98:101]
	v_mfma_f32_16x16x32_bf16 v[86:89], v[162:165], v[222:225], v[86:89]
	v_mfma_f32_16x16x32_bf16 v[82:85], v[170:173], v[222:225], v[82:85]
	v_mfma_f32_16x16x32_bf16 v[70:73], v[162:165], v[230:233], v[70:73]
	v_mfma_f32_16x16x32_bf16 v[66:69], v[170:173], v[230:233], v[66:69]
	v_mfma_f32_16x16x32_bf16 v[120:123], v[166:169], v[198:201], v[120:123]
	v_mfma_f32_16x16x32_bf16 v[116:119], v[174:177], v[198:201], v[116:119]
	v_mfma_f32_16x16x32_bf16 v[102:105], v[166:169], v[218:221], v[102:105]
	v_mfma_f32_16x16x32_bf16 v[98:101], v[174:177], v[218:221], v[98:101]
	v_mfma_f32_16x16x32_bf16 v[86:89], v[166:169], v[226:229], v[86:89]
	v_mfma_f32_16x16x32_bf16 v[82:85], v[174:177], v[226:229], v[82:85]
	v_mfma_f32_16x16x32_bf16 v[70:73], v[166:169], v[234:237], v[70:73]
	v_mfma_f32_16x16x32_bf16 v[66:69], v[174:177], v[234:237], v[66:69]
	s_setprio 0
	s_barrier
	s_add_u32 s56, s12, 0x8000
	s_addc_u32 s57, s13, 0
	s_add_i32 s16, s16, s26
	s_mov_b32 m0, s16
	ds_read_b128 v[194:197], v153 offset:49152
	ds_read_b128 v[198:201], v153 offset:50176
	ds_read_b128 v[214:217], v153 offset:51200
	ds_read_b128 v[218:221], v153 offset:52224
	ds_read_b128 v[222:225], v153 offset:53248
	ds_read_b128 v[226:229], v153 offset:54272
	ds_read_b128 v[230:233], v153 offset:55296
	ds_read_b128 v[234:237], v153 offset:56320
	global_load_lds_dwordx4 v136, s[56:57]
	s_add_i32 m0, s16, 0x2000
	s_add_u32 s12, s12, 0xc000
	s_addc_u32 s13, s13, 0
	s_add_i32 s16, s17, s26
	global_load_lds_dwordx4 v132, s[56:57]
	s_mov_b32 m0, s16
	s_nop 0
	global_load_lds_dwordx4 v136, s[12:13]
	s_add_i32 m0, s16, 0x2000
	s_nop 0
	global_load_lds_dwordx4 v132, s[12:13]
	s_mov_b32 m0, s29
	s_nop 0
	global_load_lds_dwordx4 v138, vcc
	s_mov_b32 m0, s53
	s_nop 0
	global_load_lds_dwordx4 v134, vcc
	s_waitcnt vmcnt(8)
	s_waitcnt lgkmcnt(0)
	s_barrier
	s_setprio 1
	s_waitcnt lgkmcnt(0)
	v_mfma_f32_16x16x32_bf16 v[62:65], v[144:147], v[194:197], v[62:65]
	v_mfma_f32_16x16x32_bf16 v[58:61], v[154:157], v[194:197], v[58:61]
	v_mfma_f32_16x16x32_bf16 v[46:49], v[144:147], v[214:217], v[46:49]
	v_mfma_f32_16x16x32_bf16 v[42:45], v[154:157], v[214:217], v[42:45]
	v_mfma_f32_16x16x32_bf16 v[30:33], v[144:147], v[222:225], v[30:33]
	v_mfma_f32_16x16x32_bf16 v[26:29], v[154:157], v[222:225], v[26:29]
	v_mfma_f32_16x16x32_bf16 v[14:17], v[144:147], v[230:233], v[14:17]
	v_mfma_f32_16x16x32_bf16 v[10:13], v[154:157], v[230:233], v[10:13]
	v_mfma_f32_16x16x32_bf16 v[62:65], v[148:151], v[198:201], v[62:65]
	v_mfma_f32_16x16x32_bf16 v[58:61], v[158:161], v[198:201], v[58:61]
	v_mfma_f32_16x16x32_bf16 v[46:49], v[148:151], v[218:221], v[46:49]
	v_mfma_f32_16x16x32_bf16 v[42:45], v[158:161], v[218:221], v[42:45]
	v_mfma_f32_16x16x32_bf16 v[30:33], v[148:151], v[226:229], v[30:33]
	v_mfma_f32_16x16x32_bf16 v[26:29], v[158:161], v[226:229], v[26:29]
	v_mfma_f32_16x16x32_bf16 v[14:17], v[148:151], v[234:237], v[14:17]
	v_mfma_f32_16x16x32_bf16 v[10:13], v[158:161], v[234:237], v[10:13]
	s_setprio 0
	s_setprio 1
	v_mfma_f32_16x16x32_bf16 v[54:57], v[162:165], v[194:197], v[54:57]
	v_mfma_f32_16x16x32_bf16 v[50:53], v[170:173], v[194:197], v[50:53]
	v_mfma_f32_16x16x32_bf16 v[38:41], v[162:165], v[214:217], v[38:41]
	v_mfma_f32_16x16x32_bf16 v[34:37], v[170:173], v[214:217], v[34:37]
	v_mfma_f32_16x16x32_bf16 v[22:25], v[162:165], v[222:225], v[22:25]
	v_mfma_f32_16x16x32_bf16 v[18:21], v[170:173], v[222:225], v[18:21]
	v_mfma_f32_16x16x32_bf16 v[6:9], v[162:165], v[230:233], v[6:9]
	v_mfma_f32_16x16x32_bf16 v[2:5], v[170:173], v[230:233], v[2:5]
	v_mfma_f32_16x16x32_bf16 v[54:57], v[166:169], v[198:201], v[54:57]
	v_mfma_f32_16x16x32_bf16 v[50:53], v[174:177], v[198:201], v[50:53]
	v_mfma_f32_16x16x32_bf16 v[38:41], v[166:169], v[218:221], v[38:41]
	v_mfma_f32_16x16x32_bf16 v[34:37], v[174:177], v[218:221], v[34:37]
	v_mfma_f32_16x16x32_bf16 v[22:25], v[166:169], v[226:229], v[22:25]
	v_mfma_f32_16x16x32_bf16 v[18:21], v[174:177], v[226:229], v[18:21]
	v_mfma_f32_16x16x32_bf16 v[6:9], v[166:169], v[234:237], v[6:9]
	v_mfma_f32_16x16x32_bf16 v[2:5], v[174:177], v[234:237], v[2:5]
	s_setprio 0
	s_barrier
	s_add_i32 s66, s66, 2
	s_add_u32 s62, s62, 0x10000
	s_addc_u32 s63, s63, 0
	s_add_u32 s54, s54, 0x100
	s_addc_u32 s55, s55, 0
	s_cmp_gt_u32 s66, 61
	s_cbranch_scc0 .LBB0_201
	s_and_b64 vcc, exec, s[34:35]
	s_cbranch_vccz .LBB0_204
	s_barrier

.LBB0_219:
	s_add_u32 s10, s8, 0xfff80080
	s_addc_u32 s11, s9, -1
	s_add_i32 s16, 0, 0x10000
	s_cmp_eq_u32 s25, 28
	s_cselect_b32 s13, s3, s11
	s_cselect_b32 s12, s7, s10
	v_add_u32_e32 v148, s16, v115
	s_cselect_b32 s11, s20, s24
	s_cselect_b32 s10, s22, s23
	s_add_i32 s17, 0, 0x14000
	ds_read_b128 v[144:147], v148
	ds_read_b128 v[152:155], v148 offset:1024
	ds_read_b128 v[156:159], v148 offset:2048
	ds_read_b128 v[160:163], v148 offset:3072
	v_add_u32_e32 v148, s17, v115
	ds_read_b128 v[164:167], v148
	ds_read_b128 v[168:171], v148 offset:1024
	ds_read_b128 v[172:175], v148 offset:2048
	ds_read_b128 v[176:179], v148 offset:3072
	s_add_i32 m0, s66, 0xc000
	ds_read_b128 v[194:197], v151
	ds_read_b128 v[198:201], v151 offset:1024
	ds_read_b128 v[214:217], v151 offset:2048
	ds_read_b128 v[218:221], v151 offset:3072
	ds_read_b128 v[222:225], v151 offset:4096
	ds_read_b128 v[226:229], v151 offset:5120
	ds_read_b128 v[230:233], v151 offset:6144
	ds_read_b128 v[234:237], v151 offset:7168
	global_load_lds_dwordx4 v140, s[8:9]
	s_add_i32 m0, s66, 0xe000
	s_nop 0
	global_load_lds_dwordx4 v142, s[8:9]
	s_waitcnt vmcnt(8)
	s_waitcnt lgkmcnt(0)
	s_barrier
	s_setprio 1
	s_waitcnt lgkmcnt(0)
	v_mfma_i32_16x16x64_i8 v[128:131], v[144:147], v[194:197], v[128:131]
	v_mfma_i32_16x16x64_i8 v[124:127], v[156:159], v[194:197], v[124:127]
	v_mfma_i32_16x16x64_i8 v[110:113], v[144:147], v[214:217], v[110:113]
	v_mfma_i32_16x16x64_i8 v[106:109], v[156:159], v[214:217], v[106:109]
	v_mfma_i32_16x16x64_i8 v[94:97], v[144:147], v[222:225], v[94:97]
	v_mfma_i32_16x16x64_i8 v[90:93], v[156:159], v[222:225], v[90:93]
	v_mfma_i32_16x16x64_i8 v[78:81], v[144:147], v[230:233], v[78:81]
	v_mfma_i32_16x16x64_i8 v[74:77], v[156:159], v[230:233], v[74:77]
	v_mfma_i32_16x16x64_i8 v[128:131], v[152:155], v[198:201], v[128:131]
	v_mfma_i32_16x16x64_i8 v[124:127], v[160:163], v[198:201], v[124:127]
	v_mfma_i32_16x16x64_i8 v[110:113], v[152:155], v[218:221], v[110:113]
	v_mfma_i32_16x16x64_i8 v[106:109], v[160:163], v[218:221], v[106:109]
	v_mfma_i32_16x16x64_i8 v[94:97], v[152:155], v[226:229], v[94:97]
	v_mfma_i32_16x16x64_i8 v[90:93], v[160:163], v[226:229], v[90:93]
	v_mfma_i32_16x16x64_i8 v[78:81], v[152:155], v[234:237], v[78:81]
	v_mfma_i32_16x16x64_i8 v[74:77], v[160:163], v[234:237], v[74:77]
	s_setprio 0
	s_setprio 1
	v_mfma_i32_16x16x64_i8 v[120:123], v[164:167], v[194:197], v[120:123]
	v_mfma_i32_16x16x64_i8 v[116:119], v[172:175], v[194:197], v[116:119]
	v_mfma_i32_16x16x64_i8 v[102:105], v[164:167], v[214:217], v[102:105]
	v_mfma_i32_16x16x64_i8 v[98:101], v[172:175], v[214:217], v[98:101]
	v_mfma_i32_16x16x64_i8 v[86:89], v[164:167], v[222:225], v[86:89]
	v_mfma_i32_16x16x64_i8 v[82:85], v[172:175], v[222:225], v[82:85]
	v_mfma_i32_16x16x64_i8 v[70:73], v[164:167], v[230:233], v[70:73]
	v_mfma_i32_16x16x64_i8 v[66:69], v[172:175], v[230:233], v[66:69]
	v_mfma_i32_16x16x64_i8 v[120:123], v[168:171], v[198:201], v[120:123]
	v_mfma_i32_16x16x64_i8 v[116:119], v[176:179], v[198:201], v[116:119]
	v_mfma_i32_16x16x64_i8 v[102:105], v[168:171], v[218:221], v[102:105]
	v_mfma_i32_16x16x64_i8 v[98:101], v[176:179], v[218:221], v[98:101]
	v_mfma_i32_16x16x64_i8 v[86:89], v[168:171], v[226:229], v[86:89]
	v_mfma_i32_16x16x64_i8 v[82:85], v[176:179], v[226:229], v[82:85]
	v_mfma_i32_16x16x64_i8 v[70:73], v[168:171], v[234:237], v[70:73]
	v_mfma_i32_16x16x64_i8 v[66:69], v[176:179], v[234:237], v[66:69]
	s_setprio 0
	s_barrier
	s_add_i32 s16, s16, s62
	s_mov_b32 m0, s16
	ds_read_b128 v[194:197], v151 offset:16384
	ds_read_b128 v[198:201], v151 offset:17408
	ds_read_b128 v[214:217], v151 offset:18432
	ds_read_b128 v[218:221], v151 offset:19456
	ds_read_b128 v[222:225], v151 offset:20480
	ds_read_b128 v[226:229], v151 offset:21504
	ds_read_b128 v[230:233], v151 offset:22528
	ds_read_b128 v[234:237], v151 offset:23552
	global_load_lds_dwordx4 v136, s[10:11]
	s_add_i32 m0, s16, 0x2000
	s_add_u32 s26, s10, 0x4000
	s_addc_u32 s27, s11, 0
	s_add_i32 s16, s17, s62
	global_load_lds_dwordx4 v132, s[10:11]
	s_mov_b32 m0, s16
	s_nop 0
	global_load_lds_dwordx4 v136, s[26:27]
	s_add_i32 m0, s16, 0x2000
	s_nop 0
	global_load_lds_dwordx4 v132, s[26:27]
	s_add_u32 vcc_lo, s12, s64
	s_addc_u32 vcc_hi, s13, s65
	s_mov_b32 m0, s66
	s_nop 0
	global_load_lds_dwordx4 v138, s[12:13]
	s_mov_b32 m0, s67
	s_nop 0
	global_load_lds_dwordx4 v134, s[12:13]
	s_waitcnt vmcnt(8)
	s_waitcnt lgkmcnt(0)
	s_barrier
	s_setprio 1
	s_waitcnt lgkmcnt(0)
	v_mfma_i32_16x16x64_i8 v[62:65], v[144:147], v[194:197], v[62:65]
	v_mfma_i32_16x16x64_i8 v[58:61], v[156:159], v[194:197], v[58:61]
	v_mfma_i32_16x16x64_i8 v[46:49], v[144:147], v[214:217], v[46:49]
	v_mfma_i32_16x16x64_i8 v[42:45], v[156:159], v[214:217], v[42:45]
	v_mfma_i32_16x16x64_i8 v[30:33], v[144:147], v[222:225], v[30:33]
	v_mfma_i32_16x16x64_i8 v[26:29], v[156:159], v[222:225], v[26:29]
	v_mfma_i32_16x16x64_i8 v[14:17], v[144:147], v[230:233], v[14:17]
	v_mfma_i32_16x16x64_i8 v[10:13], v[156:159], v[230:233], v[10:13]
	v_mfma_i32_16x16x64_i8 v[62:65], v[152:155], v[198:201], v[62:65]
	v_mfma_i32_16x16x64_i8 v[58:61], v[160:163], v[198:201], v[58:61]
	v_mfma_i32_16x16x64_i8 v[46:49], v[152:155], v[218:221], v[46:49]
	v_mfma_i32_16x16x64_i8 v[42:45], v[160:163], v[218:221], v[42:45]
	v_mfma_i32_16x16x64_i8 v[30:33], v[152:155], v[226:229], v[30:33]
	v_mfma_i32_16x16x64_i8 v[26:29], v[160:163], v[226:229], v[26:29]
	v_mfma_i32_16x16x64_i8 v[14:17], v[152:155], v[234:237], v[14:17]
	v_mfma_i32_16x16x64_i8 v[10:13], v[160:163], v[234:237], v[10:13]
	s_setprio 0
	s_setprio 1
	v_mfma_i32_16x16x64_i8 v[54:57], v[164:167], v[194:197], v[54:57]
	v_mfma_i32_16x16x64_i8 v[50:53], v[172:175], v[194:197], v[50:53]
	v_mfma_i32_16x16x64_i8 v[38:41], v[164:167], v[214:217], v[38:41]
	v_mfma_i32_16x16x64_i8 v[34:37], v[172:175], v[214:217], v[34:37]
	v_mfma_i32_16x16x64_i8 v[22:25], v[164:167], v[222:225], v[22:25]
	v_mfma_i32_16x16x64_i8 v[18:21], v[172:175], v[222:225], v[18:21]
	v_mfma_i32_16x16x64_i8 v[6:9], v[164:167], v[230:233], v[6:9]
	v_mfma_i32_16x16x64_i8 v[2:5], v[172:175], v[230:233], v[2:5]
	v_mfma_i32_16x16x64_i8 v[54:57], v[168:171], v[198:201], v[54:57]
	v_mfma_i32_16x16x64_i8 v[50:53], v[176:179], v[198:201], v[50:53]
	v_mfma_i32_16x16x64_i8 v[38:41], v[168:171], v[218:221], v[38:41]
	v_mfma_i32_16x16x64_i8 v[34:37], v[176:179], v[218:221], v[34:37]
	v_mfma_i32_16x16x64_i8 v[22:25], v[168:171], v[226:229], v[22:25]
	v_mfma_i32_16x16x64_i8 v[18:21], v[176:179], v[226:229], v[18:21]
	v_mfma_i32_16x16x64_i8 v[6:9], v[168:171], v[234:237], v[6:9]
	v_mfma_i32_16x16x64_i8 v[2:5], v[176:179], v[234:237], v[2:5]
	s_setprio 0
	s_barrier
	s_add_i32 s16, 0, 0x18000
	s_add_i32 s17, 0, 0x1c000
	v_add_u32_e32 v160, s16, v115
	v_add_u32_e32 v176, s17, v115
	ds_read_b128 v[144:147], v160
	ds_read_b128 v[152:155], v160 offset:1024
	ds_read_b128 v[156:159], v160 offset:2048
	ds_read_b128 v[160:163], v160 offset:3072
	ds_read_b128 v[164:167], v176
	ds_read_b128 v[168:171], v176 offset:1024
	ds_read_b128 v[172:175], v176 offset:2048
	ds_read_b128 v[176:179], v176 offset:3072
	s_add_u32 s12, s12, 0x80000
	s_addc_u32 s13, s13, 0
	s_mov_b32 m0, s74
	ds_read_b128 v[194:197], v151 offset:32768
	ds_read_b128 v[198:201], v151 offset:33792
	ds_read_b128 v[214:217], v151 offset:34816
	ds_read_b128 v[218:221], v151 offset:35840
	ds_read_b128 v[222:225], v151 offset:36864
	ds_read_b128 v[226:229], v151 offset:37888
	ds_read_b128 v[230:233], v151 offset:38912
	ds_read_b128 v[234:237], v151 offset:39936
	global_load_lds_dwordx4 v138, s[12:13]
	s_mov_b32 m0, s75
	s_nop 0
	global_load_lds_dwordx4 v134, s[12:13]
	s_waitcnt vmcnt(8)
	s_waitcnt lgkmcnt(0)
	s_barrier
	s_setprio 1
	s_waitcnt lgkmcnt(0)
	v_mfma_i32_16x16x64_i8 v[128:131], v[144:147], v[194:197], v[128:131]
	v_mfma_i32_16x16x64_i8 v[124:127], v[156:159], v[194:197], v[124:127]
	v_mfma_i32_16x16x64_i8 v[110:113], v[144:147], v[214:217], v[110:113]
	v_mfma_i32_16x16x64_i8 v[106:109], v[156:159], v[214:217], v[106:109]
	v_mfma_i32_16x16x64_i8 v[94:97], v[144:147], v[222:225], v[94:97]
	v_mfma_i32_16x16x64_i8 v[90:93], v[156:159], v[222:225], v[90:93]
	v_mfma_i32_16x16x64_i8 v[78:81], v[144:147], v[230:233], v[78:81]
	v_mfma_i32_16x16x64_i8 v[74:77], v[156:159], v[230:233], v[74:77]
	v_mfma_i32_16x16x64_i8 v[128:131], v[152:155], v[198:201], v[128:131]
	v_mfma_i32_16x16x64_i8 v[124:127], v[160:163], v[198:201], v[124:127]
	v_mfma_i32_16x16x64_i8 v[110:113], v[152:155], v[218:221], v[110:113]
	v_mfma_i32_16x16x64_i8 v[106:109], v[160:163], v[218:221], v[106:109]
	v_mfma_i32_16x16x64_i8 v[94:97], v[152:155], v[226:229], v[94:97]
	v_mfma_i32_16x16x64_i8 v[90:93], v[160:163], v[226:229], v[90:93]
	v_mfma_i32_16x16x64_i8 v[78:81], v[152:155], v[234:237], v[78:81]
	v_mfma_i32_16x16x64_i8 v[74:77], v[160:163], v[234:237], v[74:77]
	s_setprio 0
	s_setprio 1
	v_mfma_i32_16x16x64_i8 v[120:123], v[164:167], v[194:197], v[120:123]
	v_mfma_i32_16x16x64_i8 v[116:119], v[172:175], v[194:197], v[116:119]
	v_mfma_i32_16x16x64_i8 v[102:105], v[164:167], v[214:217], v[102:105]
	v_mfma_i32_16x16x64_i8 v[98:101], v[172:175], v[214:217], v[98:101]
	v_mfma_i32_16x16x64_i8 v[86:89], v[164:167], v[222:225], v[86:89]
	v_mfma_i32_16x16x64_i8 v[82:85], v[172:175], v[222:225], v[82:85]
	v_mfma_i32_16x16x64_i8 v[70:73], v[164:167], v[230:233], v[70:73]
	v_mfma_i32_16x16x64_i8 v[66:69], v[172:175], v[230:233], v[66:69]
	v_mfma_i32_16x16x64_i8 v[120:123], v[168:171], v[198:201], v[120:123]
	v_mfma_i32_16x16x64_i8 v[116:119], v[176:179], v[198:201], v[116:119]
	v_mfma_i32_16x16x64_i8 v[102:105], v[168:171], v[218:221], v[102:105]
	v_mfma_i32_16x16x64_i8 v[98:101], v[176:179], v[218:221], v[98:101]
	v_mfma_i32_16x16x64_i8 v[86:89], v[168:171], v[226:229], v[86:89]
	v_mfma_i32_16x16x64_i8 v[82:85], v[176:179], v[226:229], v[82:85]
	v_mfma_i32_16x16x64_i8 v[70:73], v[168:171], v[234:237], v[70:73]
	v_mfma_i32_16x16x64_i8 v[66:69], v[176:179], v[234:237], v[66:69]
	s_setprio 0
	s_barrier
	s_add_u32 s12, s10, 0x8000
	s_addc_u32 s13, s11, 0
	s_add_i32 s16, s16, s62
	s_mov_b32 m0, s16
	ds_read_b128 v[194:197], v151 offset:49152
	ds_read_b128 v[198:201], v151 offset:50176
	ds_read_b128 v[214:217], v151 offset:51200
	ds_read_b128 v[218:221], v151 offset:52224
	ds_read_b128 v[222:225], v151 offset:53248
	ds_read_b128 v[226:229], v151 offset:54272
	ds_read_b128 v[230:233], v151 offset:55296
	ds_read_b128 v[234:237], v151 offset:56320
	global_load_lds_dwordx4 v136, s[12:13]
	s_add_i32 m0, s16, 0x2000
	s_add_u32 s10, s10, 0xc000
	s_addc_u32 s11, s11, 0
	global_load_lds_dwordx4 v132, s[12:13]
	s_add_i32 s12, s17, s62
	s_mov_b32 m0, s12
	s_nop 0
	global_load_lds_dwordx4 v136, s[10:11]
	s_add_i32 m0, s12, 0x2000
	s_nop 0
	global_load_lds_dwordx4 v132, s[10:11]
	s_mov_b32 m0, s76
	s_nop 0
	global_load_lds_dwordx4 v138, vcc
	s_mov_b32 m0, s77
	s_nop 0
	global_load_lds_dwordx4 v134, vcc
	s_waitcnt vmcnt(8)
	s_waitcnt lgkmcnt(0)
	s_barrier
	s_setprio 1
	s_waitcnt lgkmcnt(0)
	v_mfma_i32_16x16x64_i8 v[62:65], v[144:147], v[194:197], v[62:65]
	v_mfma_i32_16x16x64_i8 v[58:61], v[156:159], v[194:197], v[58:61]
	v_mfma_i32_16x16x64_i8 v[46:49], v[144:147], v[214:217], v[46:49]
	v_mfma_i32_16x16x64_i8 v[42:45], v[156:159], v[214:217], v[42:45]
	v_mfma_i32_16x16x64_i8 v[30:33], v[144:147], v[222:225], v[30:33]
	v_mfma_i32_16x16x64_i8 v[26:29], v[156:159], v[222:225], v[26:29]
	v_mfma_i32_16x16x64_i8 v[14:17], v[144:147], v[230:233], v[14:17]
	v_mfma_i32_16x16x64_i8 v[10:13], v[156:159], v[230:233], v[10:13]
	v_mfma_i32_16x16x64_i8 v[62:65], v[152:155], v[198:201], v[62:65]
	v_mfma_i32_16x16x64_i8 v[58:61], v[160:163], v[198:201], v[58:61]
	v_mfma_i32_16x16x64_i8 v[46:49], v[152:155], v[218:221], v[46:49]
	v_mfma_i32_16x16x64_i8 v[42:45], v[160:163], v[218:221], v[42:45]
	v_mfma_i32_16x16x64_i8 v[30:33], v[152:155], v[226:229], v[30:33]
	v_mfma_i32_16x16x64_i8 v[26:29], v[160:163], v[226:229], v[26:29]
	v_mfma_i32_16x16x64_i8 v[14:17], v[152:155], v[234:237], v[14:17]
	v_mfma_i32_16x16x64_i8 v[10:13], v[160:163], v[234:237], v[10:13]
	s_setprio 0
	s_setprio 1
	v_mfma_i32_16x16x64_i8 v[54:57], v[164:167], v[194:197], v[54:57]
	v_mfma_i32_16x16x64_i8 v[50:53], v[172:175], v[194:197], v[50:53]
	v_mfma_i32_16x16x64_i8 v[38:41], v[164:167], v[214:217], v[38:41]
	v_mfma_i32_16x16x64_i8 v[34:37], v[172:175], v[214:217], v[34:37]
	v_mfma_i32_16x16x64_i8 v[22:25], v[164:167], v[222:225], v[22:25]
	v_mfma_i32_16x16x64_i8 v[18:21], v[172:175], v[222:225], v[18:21]
	v_mfma_i32_16x16x64_i8 v[6:9], v[164:167], v[230:233], v[6:9]
	v_mfma_i32_16x16x64_i8 v[2:5], v[172:175], v[230:233], v[2:5]
	v_mfma_i32_16x16x64_i8 v[54:57], v[168:171], v[198:201], v[54:57]
	v_mfma_i32_16x16x64_i8 v[50:53], v[176:179], v[198:201], v[50:53]
	v_mfma_i32_16x16x64_i8 v[38:41], v[168:171], v[218:221], v[38:41]
	v_mfma_i32_16x16x64_i8 v[34:37], v[176:179], v[218:221], v[34:37]
	v_mfma_i32_16x16x64_i8 v[22:25], v[168:171], v[226:229], v[22:25]
	v_mfma_i32_16x16x64_i8 v[18:21], v[176:179], v[226:229], v[18:21]
	v_mfma_i32_16x16x64_i8 v[6:9], v[168:171], v[234:237], v[6:9]
	v_mfma_i32_16x16x64_i8 v[2:5], v[176:179], v[234:237], v[2:5]
	s_setprio 0
	s_barrier
	s_add_i32 s25, s25, 2
	s_add_u32 s23, s23, 0x10000
	s_addc_u32 s24, s24, 0
	s_add_u32 s8, s8, 0x100
	s_addc_u32 s9, s9, 0
	s_cmp_gt_u32 s25, 29
	s_cbranch_scc0 .LBB0_219
	s_and_b64 vcc, exec, s[52:53]
	s_cbranch_vccz .LBB0_222
	s_barrier

.LBB0_567:
	s_add_u32 s12, s44, 0xfff00080
	s_addc_u32 s13, s45, -1
	s_add_i32 s16, 0, 0x10000
	s_cmp_eq_u32 s56, 60
	s_cselect_b32 s47, s37, s13
	s_cselect_b32 s46, s52, s12
	v_add_u32_e32 v144, s16, v115
	s_cselect_b32 s13, s35, s55
	s_cselect_b32 s12, s53, s54
	s_add_i32 s57, 0, 0x14000
	ds_read_b128 v[148:151], v144
	ds_read_b128 v[152:155], v144 offset:1024
	ds_read_b128 v[156:159], v144 offset:2048
	ds_read_b128 v[160:163], v144 offset:3072
	v_add_u32_e32 v144, s57, v115
	ds_read_b128 v[164:167], v144
	ds_read_b128 v[168:171], v144 offset:1024
	ds_read_b128 v[172:175], v144 offset:2048
	ds_read_b128 v[176:179], v144 offset:3072
	s_add_i32 m0, s24, 0xc000
	ds_read_b128 v[182:185], v147
	ds_read_b128 v[194:197], v147 offset:1024
	ds_read_b128 v[198:201], v147 offset:2048
	ds_read_b128 v[214:217], v147 offset:3072
	ds_read_b128 v[218:221], v147 offset:4096
	ds_read_b128 v[222:225], v147 offset:5120
	ds_read_b128 v[226:229], v147 offset:6144
	ds_read_b128 v[230:233], v147 offset:7168
	global_load_lds_dwordx4 v140, s[44:45]
	s_add_i32 m0, s24, 0xe000
	s_nop 0
	global_load_lds_dwordx4 v142, s[44:45]
	s_waitcnt vmcnt(8)
	s_waitcnt lgkmcnt(0)
	s_barrier
	s_setprio 1
	s_waitcnt lgkmcnt(0)
	v_mfma_f32_16x16x32_bf16 v[128:131], v[148:151], v[182:185], v[128:131]
	v_mfma_f32_16x16x32_bf16 v[124:127], v[156:159], v[182:185], v[124:127]
	v_mfma_f32_16x16x32_bf16 v[120:123], v[148:151], v[198:201], v[120:123]
	v_mfma_f32_16x16x32_bf16 v[110:113], v[156:159], v[198:201], v[110:113]
	v_mfma_f32_16x16x32_bf16 v[102:105], v[148:151], v[218:221], v[102:105]
	v_mfma_f32_16x16x32_bf16 v[94:97], v[156:159], v[218:221], v[94:97]
	v_mfma_f32_16x16x32_bf16 v[86:89], v[148:151], v[226:229], v[86:89]
	v_mfma_f32_16x16x32_bf16 v[78:81], v[156:159], v[226:229], v[78:81]
	v_mfma_f32_16x16x32_bf16 v[128:131], v[152:155], v[194:197], v[128:131]
	v_mfma_f32_16x16x32_bf16 v[124:127], v[160:163], v[194:197], v[124:127]
	v_mfma_f32_16x16x32_bf16 v[120:123], v[152:155], v[214:217], v[120:123]
	v_mfma_f32_16x16x32_bf16 v[110:113], v[160:163], v[214:217], v[110:113]
	v_mfma_f32_16x16x32_bf16 v[102:105], v[152:155], v[222:225], v[102:105]
	v_mfma_f32_16x16x32_bf16 v[94:97], v[160:163], v[222:225], v[94:97]
	v_mfma_f32_16x16x32_bf16 v[86:89], v[152:155], v[230:233], v[86:89]
	v_mfma_f32_16x16x32_bf16 v[78:81], v[160:163], v[230:233], v[78:81]
	s_setprio 0
	s_setprio 1
	v_mfma_f32_16x16x32_bf16 v[116:119], v[164:167], v[182:185], v[116:119]
	v_mfma_f32_16x16x32_bf16 v[106:109], v[172:175], v[182:185], v[106:109]
	v_mfma_f32_16x16x32_bf16 v[98:101], v[164:167], v[198:201], v[98:101]
	v_mfma_f32_16x16x32_bf16 v[90:93], v[172:175], v[198:201], v[90:93]
	v_mfma_f32_16x16x32_bf16 v[82:85], v[164:167], v[218:221], v[82:85]
	v_mfma_f32_16x16x32_bf16 v[74:77], v[172:175], v[218:221], v[74:77]
	v_mfma_f32_16x16x32_bf16 v[70:73], v[164:167], v[226:229], v[70:73]
	v_mfma_f32_16x16x32_bf16 v[66:69], v[172:175], v[226:229], v[66:69]
	v_mfma_f32_16x16x32_bf16 v[116:119], v[168:171], v[194:197], v[116:119]
	v_mfma_f32_16x16x32_bf16 v[106:109], v[176:179], v[194:197], v[106:109]
	v_mfma_f32_16x16x32_bf16 v[98:101], v[168:171], v[214:217], v[98:101]
	v_mfma_f32_16x16x32_bf16 v[90:93], v[176:179], v[214:217], v[90:93]
	v_mfma_f32_16x16x32_bf16 v[82:85], v[168:171], v[222:225], v[82:85]
	v_mfma_f32_16x16x32_bf16 v[74:77], v[176:179], v[222:225], v[74:77]
	v_mfma_f32_16x16x32_bf16 v[70:73], v[168:171], v[230:233], v[70:73]
	v_mfma_f32_16x16x32_bf16 v[66:69], v[176:179], v[230:233], v[66:69]
	s_setprio 0
	s_barrier
	s_add_i32 s16, s16, s23
	s_mov_b32 m0, s16
	ds_read_b128 v[182:185], v147 offset:16384
	ds_read_b128 v[194:197], v147 offset:17408
	ds_read_b128 v[198:201], v147 offset:18432
	ds_read_b128 v[214:217], v147 offset:19456
	ds_read_b128 v[218:221], v147 offset:20480
	ds_read_b128 v[222:225], v147 offset:21504
	ds_read_b128 v[226:229], v147 offset:22528
	ds_read_b128 v[230:233], v147 offset:23552
	global_load_lds_dwordx4 v136, s[12:13]
	s_add_i32 m0, s16, 0x2000
	s_add_u32 s16, s12, 0x4000
	s_addc_u32 s17, s13, 0
	s_add_i32 s57, s57, s23
	global_load_lds_dwordx4 v132, s[12:13]
	s_mov_b32 m0, s57
	s_nop 0
	global_load_lds_dwordx4 v136, s[16:17]
	s_add_i32 m0, s57, 0x2000
	s_nop 0
	global_load_lds_dwordx4 v132, s[16:17]
	s_add_u32 vcc_lo, s46, s64
	s_addc_u32 vcc_hi, s47, s65
	s_mov_b32 m0, s24
	s_nop 0
	global_load_lds_dwordx4 v138, s[46:47]
	s_mov_b32 m0, s25
	s_nop 0
	global_load_lds_dwordx4 v134, s[46:47]
	s_waitcnt vmcnt(8)
	s_waitcnt lgkmcnt(0)
	s_barrier
	s_setprio 1
	s_waitcnt lgkmcnt(0)
	v_mfma_f32_16x16x32_bf16 v[62:65], v[148:151], v[182:185], v[62:65]
	v_mfma_f32_16x16x32_bf16 v[58:61], v[156:159], v[182:185], v[58:61]
	v_mfma_f32_16x16x32_bf16 v[54:57], v[148:151], v[198:201], v[54:57]
	v_mfma_f32_16x16x32_bf16 v[46:49], v[156:159], v[198:201], v[46:49]
	v_mfma_f32_16x16x32_bf16 v[38:41], v[148:151], v[218:221], v[38:41]
	v_mfma_f32_16x16x32_bf16 v[30:33], v[156:159], v[218:221], v[30:33]
	v_mfma_f32_16x16x32_bf16 v[22:25], v[148:151], v[226:229], v[22:25]
	v_mfma_f32_16x16x32_bf16 v[14:17], v[156:159], v[226:229], v[14:17]
	v_mfma_f32_16x16x32_bf16 v[62:65], v[152:155], v[194:197], v[62:65]
	v_mfma_f32_16x16x32_bf16 v[58:61], v[160:163], v[194:197], v[58:61]
	v_mfma_f32_16x16x32_bf16 v[54:57], v[152:155], v[214:217], v[54:57]
	v_mfma_f32_16x16x32_bf16 v[46:49], v[160:163], v[214:217], v[46:49]
	v_mfma_f32_16x16x32_bf16 v[38:41], v[152:155], v[222:225], v[38:41]
	v_mfma_f32_16x16x32_bf16 v[30:33], v[160:163], v[222:225], v[30:33]
	v_mfma_f32_16x16x32_bf16 v[22:25], v[152:155], v[230:233], v[22:25]
	v_mfma_f32_16x16x32_bf16 v[14:17], v[160:163], v[230:233], v[14:17]
	s_setprio 0
	s_setprio 1
	v_mfma_f32_16x16x32_bf16 v[50:53], v[164:167], v[182:185], v[50:53]
	v_mfma_f32_16x16x32_bf16 v[42:45], v[172:175], v[182:185], v[42:45]
	v_mfma_f32_16x16x32_bf16 v[34:37], v[164:167], v[198:201], v[34:37]
	v_mfma_f32_16x16x32_bf16 v[26:29], v[172:175], v[198:201], v[26:29]
	v_mfma_f32_16x16x32_bf16 v[18:21], v[164:167], v[218:221], v[18:21]
	v_mfma_f32_16x16x32_bf16 v[10:13], v[172:175], v[218:221], v[10:13]
	v_mfma_f32_16x16x32_bf16 v[6:9], v[164:167], v[226:229], v[6:9]
	v_mfma_f32_16x16x32_bf16 v[2:5], v[172:175], v[226:229], v[2:5]
	v_mfma_f32_16x16x32_bf16 v[50:53], v[168:171], v[194:197], v[50:53]
	v_mfma_f32_16x16x32_bf16 v[42:45], v[176:179], v[194:197], v[42:45]
	v_mfma_f32_16x16x32_bf16 v[34:37], v[168:171], v[214:217], v[34:37]
	v_mfma_f32_16x16x32_bf16 v[26:29], v[176:179], v[214:217], v[26:29]
	v_mfma_f32_16x16x32_bf16 v[18:21], v[168:171], v[222:225], v[18:21]
	v_mfma_f32_16x16x32_bf16 v[10:13], v[176:179], v[222:225], v[10:13]
	v_mfma_f32_16x16x32_bf16 v[6:9], v[168:171], v[230:233], v[6:9]
	v_mfma_f32_16x16x32_bf16 v[2:5], v[176:179], v[230:233], v[2:5]
	s_setprio 0
	s_barrier
; #define PG8_STAGE(bufoff, gbase, voff) do { _Pragma("unroll") for (int _i = 0; _i < 2; ++_i) \
;         __builtin_amdgcn_global_load_lds((const unsigned*)((const char*)(gbase) + (voff)[_i]), (PG8_LAS unsigned*)(lds + (bufoff) + ldsw + _i * 8192), 16, 0, 0); } while (0)
; #define PG8_LDA(dst, b, h) do { _Pragma("unroll") for (int m = 0; m < 4; ++m) _Pragma("unroll") for (int k = 0; k < 2; ++k) dst[m][k] = *(const PG8_LAS frag_t*)(lds + PG8_SA(b, h) + aoff + m * 2048 + k * 1024); } while (0)
; #define PG8_LDB(dst, b, h) do { _Pragma("unroll") for (int n = 0; n < 2; ++n) _Pragma("unroll") for (int k = 0; k < 2; ++k) dst[n][k] = *(const PG8_LAS frag_t*)(lds + PG8_SB(b, h) + boff + n * 2048 + k * 1024); } while (0)
; #define PG8_MMA(ai, bj, At, Bt) do { __builtin_amdgcn_s_setprio(1); _Pragma("unroll") for (int m = 0; m < 4; ++m) _Pragma("unroll") for (int n = 0; n < 2; ++n) _Pragma("unroll") for (int k = 0; k < 2; ++k) \
;         acc[ai][bj][m][n] = MT<I8>::mma(Bt[n][k], At[m][k], acc[ai][bj][m][n]); __builtin_amdgcn_s_setprio(0); } while (0)
; #define PG8_WAIT_V(n) asm volatile("s_waitcnt vmcnt(" #n ")" ::: "memory")
; #define PG8_WAIT_L(n) asm volatile("s_waitcnt lgkmcnt(" #n ")" ::: "memory")
; #define PG8_BAR __builtin_amdgcn_s_barrier()
; #define PG8_SCHED __builtin_amdgcn_sched_barrier(0)
; template <class Epi, class Sched, bool ALIGN_EPI = false, bool SP2 = false, bool TILED_A = false, bool TILED_B = false, bool I8 = false>
; __device__ __forceinline__ void gemm_phase(PG8_LAS unsigned char* lds, const Gemm g, const Sched& S, const Epi& E) {
;     ...
;             PG8_LDB(B0, 1, 0); PG8_LDB(B1, 1, 1); PG8_SCHED; PG8_LDA(At, 1, 0); PG8_STAGE(PG8_SA(0, 1), a2 + hstepA, voffA);
;             PG8_WAIT_V(8); PG8_WAIT_L(0); PG8_BAR; PG8_MMA(0, 0, At, B0); PG8_MMA(0, 1, At, B1); PG8_BAR; PG8_SCHED;
;             PG8_LDA(At, 1, 1); PG8_STAGE(PG8_SB(1, 0), b3, voffB); PG8_STAGE(PG8_SB(1, 1), b3 + hstepB, voffB); PG8_STAGE(PG8_SA(1, 0), a3, voffA);
;             PG8_WAIT_V(8); PG8_WAIT_L(0); PG8_BAR; PG8_MMA(1, 0, At, B0); PG8_MMA(1, 1, At, B1); PG8_BAR; PG8_SCHED;
	s_add_i32 s57, 0, 0x18000
	s_add_i32 s58, 0, 0x1c000
	v_add_u32_e32 v160, s57, v115
	v_add_u32_e32 v176, s58, v115
	ds_read_b128 v[148:151], v160
	ds_read_b128 v[152:155], v160 offset:1024
	ds_read_b128 v[156:159], v160 offset:2048
	ds_read_b128 v[160:163], v160 offset:3072
	ds_read_b128 v[164:167], v176
	ds_read_b128 v[168:171], v176 offset:1024
	ds_read_b128 v[172:175], v176 offset:2048
	ds_read_b128 v[176:179], v176 offset:3072
	s_add_u32 s16, s46, 0x100000
	s_addc_u32 s17, s47, 0
	s_mov_b32 m0, s26
	ds_read_b128 v[182:185], v147 offset:32768
	ds_read_b128 v[194:197], v147 offset:33792
	ds_read_b128 v[198:201], v147 offset:34816
	ds_read_b128 v[214:217], v147 offset:35840
	ds_read_b128 v[218:221], v147 offset:36864
	ds_read_b128 v[222:225], v147 offset:37888
	ds_read_b128 v[226:229], v147 offset:38912
	ds_read_b128 v[230:233], v147 offset:39936
	global_load_lds_dwordx4 v138, s[16:17]
	s_mov_b32 m0, s27
	s_nop 0
	global_load_lds_dwordx4 v134, s[16:17]
	s_waitcnt vmcnt(8)
	s_waitcnt lgkmcnt(0)
	s_barrier
	s_setprio 1
	s_waitcnt lgkmcnt(0)
	v_mfma_f32_16x16x32_bf16 v[128:131], v[148:151], v[182:185], v[128:131]
	v_mfma_f32_16x16x32_bf16 v[124:127], v[156:159], v[182:185], v[124:127]
	v_mfma_f32_16x16x32_bf16 v[120:123], v[148:151], v[198:201], v[120:123]
	v_mfma_f32_16x16x32_bf16 v[110:113], v[156:159], v[198:201], v[110:113]
	v_mfma_f32_16x16x32_bf16 v[102:105], v[148:151], v[218:221], v[102:105]
	v_mfma_f32_16x16x32_bf16 v[94:97], v[156:159], v[218:221], v[94:97]
	v_mfma_f32_16x16x32_bf16 v[86:89], v[148:151], v[226:229], v[86:89]
	v_mfma_f32_16x16x32_bf16 v[78:81], v[156:159], v[226:229], v[78:81]
	v_mfma_f32_16x16x32_bf16 v[128:131], v[152:155], v[194:197], v[128:131]
	v_mfma_f32_16x16x32_bf16 v[124:127], v[160:163], v[194:197], v[124:127]
	v_mfma_f32_16x16x32_bf16 v[120:123], v[152:155], v[214:217], v[120:123]
	v_mfma_f32_16x16x32_bf16 v[110:113], v[160:163], v[214:217], v[110:113]
	v_mfma_f32_16x16x32_bf16 v[102:105], v[152:155], v[222:225], v[102:105]
	v_mfma_f32_16x16x32_bf16 v[94:97], v[160:163], v[222:225], v[94:97]
	v_mfma_f32_16x16x32_bf16 v[86:89], v[152:155], v[230:233], v[86:89]
	v_mfma_f32_16x16x32_bf16 v[78:81], v[160:163], v[230:233], v[78:81]
	s_setprio 0
	s_setprio 1
	v_mfma_f32_16x16x32_bf16 v[116:119], v[164:167], v[182:185], v[116:119]
	v_mfma_f32_16x16x32_bf16 v[106:109], v[172:175], v[182:185], v[106:109]
	v_mfma_f32_16x16x32_bf16 v[98:101], v[164:167], v[198:201], v[98:101]
	v_mfma_f32_16x16x32_bf16 v[90:93], v[172:175], v[198:201], v[90:93]
	v_mfma_f32_16x16x32_bf16 v[82:85], v[164:167], v[218:221], v[82:85]
	v_mfma_f32_16x16x32_bf16 v[74:77], v[172:175], v[218:221], v[74:77]
	v_mfma_f32_16x16x32_bf16 v[70:73], v[164:167], v[226:229], v[70:73]
	v_mfma_f32_16x16x32_bf16 v[66:69], v[172:175], v[226:229], v[66:69]
	v_mfma_f32_16x16x32_bf16 v[116:119], v[168:171], v[194:197], v[116:119]
	v_mfma_f32_16x16x32_bf16 v[106:109], v[176:179], v[194:197], v[106:109]
	v_mfma_f32_16x16x32_bf16 v[98:101], v[168:171], v[214:217], v[98:101]
	v_mfma_f32_16x16x32_bf16 v[90:93], v[176:179], v[214:217], v[90:93]
	v_mfma_f32_16x16x32_bf16 v[82:85], v[168:171], v[222:225], v[82:85]
	v_mfma_f32_16x16x32_bf16 v[74:77], v[176:179], v[222:225], v[74:77]
	v_mfma_f32_16x16x32_bf16 v[70:73], v[168:171], v[230:233], v[70:73]
	v_mfma_f32_16x16x32_bf16 v[66:69], v[176:179], v[230:233], v[66:69]
	s_setprio 0
	s_barrier
	s_add_u32 s16, s12, 0x8000
	s_addc_u32 s17, s13, 0
	s_add_i32 s46, s57, s23
	s_mov_b32 m0, s46
	ds_read_b128 v[182:185], v147 offset:49152
	ds_read_b128 v[194:197], v147 offset:50176
	ds_read_b128 v[198:201], v147 offset:51200
	ds_read_b128 v[214:217], v147 offset:52224
	ds_read_b128 v[218:221], v147 offset:53248
	ds_read_b128 v[222:225], v147 offset:54272
	ds_read_b128 v[226:229], v147 offset:55296
	ds_read_b128 v[230:233], v147 offset:56320
	global_load_lds_dwordx4 v136, s[16:17]
	s_add_i32 m0, s46, 0x2000
	s_add_u32 s12, s12, 0xc000
	s_addc_u32 s13, s13, 0
	global_load_lds_dwordx4 v132, s[16:17]
	s_add_i32 s16, s58, s23
	s_mov_b32 m0, s16
	s_nop 0
	global_load_lds_dwordx4 v136, s[12:13]
	s_add_i32 m0, s16, 0x2000
	s_nop 0
	global_load_lds_dwordx4 v132, s[12:13]
	s_mov_b32 m0, s28
	s_nop 0
	global_load_lds_dwordx4 v138, vcc
	s_mov_b32 m0, s29
	s_nop 0
	global_load_lds_dwordx4 v134, vcc
	s_waitcnt vmcnt(8)
	s_waitcnt lgkmcnt(0)
	s_barrier
	s_setprio 1
	s_waitcnt lgkmcnt(0)
	v_mfma_f32_16x16x32_bf16 v[62:65], v[148:151], v[182:185], v[62:65]
	v_mfma_f32_16x16x32_bf16 v[58:61], v[156:159], v[182:185], v[58:61]
	v_mfma_f32_16x16x32_bf16 v[54:57], v[148:151], v[198:201], v[54:57]
	v_mfma_f32_16x16x32_bf16 v[46:49], v[156:159], v[198:201], v[46:49]
	v_mfma_f32_16x16x32_bf16 v[38:41], v[148:151], v[218:221], v[38:41]
	v_mfma_f32_16x16x32_bf16 v[30:33], v[156:159], v[218:221], v[30:33]
	v_mfma_f32_16x16x32_bf16 v[22:25], v[148:151], v[226:229], v[22:25]
	v_mfma_f32_16x16x32_bf16 v[14:17], v[156:159], v[226:229], v[14:17]
	v_mfma_f32_16x16x32_bf16 v[62:65], v[152:155], v[194:197], v[62:65]
	v_mfma_f32_16x16x32_bf16 v[58:61], v[160:163], v[194:197], v[58:61]
	v_mfma_f32_16x16x32_bf16 v[54:57], v[152:155], v[214:217], v[54:57]
	v_mfma_f32_16x16x32_bf16 v[46:49], v[160:163], v[214:217], v[46:49]
	v_mfma_f32_16x16x32_bf16 v[38:41], v[152:155], v[222:225], v[38:41]
	v_mfma_f32_16x16x32_bf16 v[30:33], v[160:163], v[222:225], v[30:33]
	v_mfma_f32_16x16x32_bf16 v[22:25], v[152:155], v[230:233], v[22:25]
	v_mfma_f32_16x16x32_bf16 v[14:17], v[160:163], v[230:233], v[14:17]
	s_setprio 0
	s_setprio 1
	v_mfma_f32_16x16x32_bf16 v[50:53], v[164:167], v[182:185], v[50:53]
	v_mfma_f32_16x16x32_bf16 v[42:45], v[172:175], v[182:185], v[42:45]
	v_mfma_f32_16x16x32_bf16 v[34:37], v[164:167], v[198:201], v[34:37]
	v_mfma_f32_16x16x32_bf16 v[26:29], v[172:175], v[198:201], v[26:29]
	v_mfma_f32_16x16x32_bf16 v[18:21], v[164:167], v[218:221], v[18:21]
	v_mfma_f32_16x16x32_bf16 v[10:13], v[172:175], v[218:221], v[10:13]
	v_mfma_f32_16x16x32_bf16 v[6:9], v[164:167], v[226:229], v[6:9]
	v_mfma_f32_16x16x32_bf16 v[2:5], v[172:175], v[226:229], v[2:5]
	v_mfma_f32_16x16x32_bf16 v[50:53], v[168:171], v[194:197], v[50:53]
	v_mfma_f32_16x16x32_bf16 v[42:45], v[176:179], v[194:197], v[42:45]
	v_mfma_f32_16x16x32_bf16 v[34:37], v[168:171], v[214:217], v[34:37]
	v_mfma_f32_16x16x32_bf16 v[26:29], v[176:179], v[214:217], v[26:29]
	v_mfma_f32_16x16x32_bf16 v[18:21], v[168:171], v[222:225], v[18:21]
	v_mfma_f32_16x16x32_bf16 v[10:13], v[176:179], v[222:225], v[10:13]
	v_mfma_f32_16x16x32_bf16 v[6:9], v[168:171], v[230:233], v[6:9]
	v_mfma_f32_16x16x32_bf16 v[2:5], v[176:179], v[230:233], v[2:5]
	s_setprio 0
	s_barrier
	s_add_i32 s56, s56, 2
	s_add_u32 s54, s54, 0x10000
	s_addc_u32 s55, s55, 0
	s_add_u32 s44, s44, 0x100
	s_addc_u32 s45, s45, 0
	s_cmp_gt_u32 s56, 61
	s_cbranch_scc0 .LBB0_567
	s_and_b64 vcc, exec, s[10:11]
	s_mov_b32 s52, 0x3d201000
	s_mov_b32 s56, 0x437f0000
	s_cbranch_vccz .LBB0_570
	s_barrier

; #define PG8_STAGE(bufoff, gbase, voff) do { _Pragma("unroll") for (int _i = 0; _i < 2; ++_i) \
;         __builtin_amdgcn_global_load_lds((const unsigned*)((const char*)(gbase) + (voff)[_i]), (PG8_LAS unsigned*)(lds + (bufoff) + ldsw + _i * 8192), 16, 0, 0); } while (0)
; #define PG8_LDA(dst, b, h) do { _Pragma("unroll") for (int m = 0; m < 4; ++m) _Pragma("unroll") for (int k = 0; k < 2; ++k) dst[m][k] = *(const PG8_LAS frag_t*)(lds + PG8_SA(b, h) + aoff + m * 2048 + k * 1024); } while (0)
; #define PG8_LDB(dst, b, h) do { _Pragma("unroll") for (int n = 0; n < 2; ++n) _Pragma("unroll") for (int k = 0; k < 2; ++k) dst[n][k] = *(const PG8_LAS frag_t*)(lds + PG8_SB(b, h) + boff + n * 2048 + k * 1024); } while (0)
; #define PG8_MMA(ai, bj, At, Bt) do { __builtin_amdgcn_s_setprio(1); _Pragma("unroll") for (int m = 0; m < 4; ++m) _Pragma("unroll") for (int n = 0; n < 2; ++n) _Pragma("unroll") for (int k = 0; k < 2; ++k) \
;         acc[ai][bj][m][n] = MT<I8>::mma(Bt[n][k], At[m][k], acc[ai][bj][m][n]); __builtin_amdgcn_s_setprio(0); } while (0)
; #define PG8_WAIT_V(n) asm volatile("s_waitcnt vmcnt(" #n ")" ::: "memory")
; #define PG8_WAIT_L(n) asm volatile("s_waitcnt lgkmcnt(" #n ")" ::: "memory")
; #define PG8_BAR __builtin_amdgcn_s_barrier()
; #define PG8_SCHED __builtin_amdgcn_sched_barrier(0)
; template <class Epi, class Sched, bool ALIGN_EPI = false, bool SP2 = false, bool TILED_A = false, bool TILED_B = false, bool I8 = false>
; __device__ __forceinline__ void gemm_phase(PG8_LAS unsigned char* lds, const Gemm g, const Sched& S, const Epi& E) {
;     ...
;             PG8_LDB(B0, 0, 0); PG8_LDB(B1, 0, 1); PG8_SCHED; PG8_LDA(At, 0, 0); PG8_STAGE(PG8_SA(1, 1), a1 + hstepA, voffA);
;             PG8_WAIT_V(8); PG8_WAIT_L(0); PG8_BAR; PG8_MMA(0, 0, At, B0); PG8_MMA(0, 1, At, B1); PG8_BAR; PG8_SCHED;
;             PG8_LDA(At, 0, 1); PG8_STAGE(PG8_SB(0, 0), b2, voffB); PG8_STAGE(PG8_SB(0, 1), b2 + hstepB, voffB); PG8_STAGE(PG8_SA(0, 0), a2, voffA);
;             PG8_WAIT_V(8); PG8_WAIT_L(0); PG8_BAR; PG8_MMA(1, 0, At, B0); PG8_MMA(1, 1, At, B1); PG8_BAR; PG8_SCHED;
.LBB0_718:
	s_add_u32 s10, s6, 0xfff80080
	s_addc_u32 s11, s7, -1
	s_add_i32 s16, 0, 0x10000
	s_cmp_eq_u32 s53, 28
	s_cselect_b32 s13, s3, s11
	s_cselect_b32 s12, s9, s10
	v_add_u32_e32 v145, s16, v115
	s_cselect_b32 s11, s22, s48
	s_cselect_b32 s10, s23, s24
	s_add_i32 s55, 0, 0x14000
	ds_read_b128 v[146:149], v145
	ds_read_b128 v[156:159], v145 offset:1024
	ds_read_b128 v[160:163], v145 offset:2048
	ds_read_b128 v[164:167], v145 offset:3072
	v_add_u32_e32 v145, s55, v115
	ds_read_b128 v[168:171], v145
	ds_read_b128 v[172:175], v145 offset:1024
	ds_read_b128 v[176:179], v145 offset:2048
	ds_read_b128 v[182:185], v145 offset:3072
	s_add_i32 m0, s29, 0xc000
	ds_read_b128 v[194:197], v154
	ds_read_b128 v[198:201], v154 offset:1024
	ds_read_b128 v[214:217], v154 offset:2048
	ds_read_b128 v[218:221], v154 offset:3072
	ds_read_b128 v[222:225], v154 offset:4096
	ds_read_b128 v[226:229], v154 offset:5120
	ds_read_b128 v[230:233], v154 offset:6144
	ds_read_b128 v[234:237], v154 offset:7168
	global_load_lds_dwordx4 v140, s[6:7]
	s_add_i32 m0, s29, 0xe000
	s_nop 0
	global_load_lds_dwordx4 v142, s[6:7]
	s_waitcnt vmcnt(8)
	s_waitcnt lgkmcnt(0)
	s_barrier
	s_setprio 1
	s_waitcnt lgkmcnt(0)
	v_mfma_i32_16x16x64_i8 v[128:131], v[146:149], v[194:197], v[128:131]
	v_mfma_i32_16x16x64_i8 v[124:127], v[160:163], v[194:197], v[124:127]
	v_mfma_i32_16x16x64_i8 v[110:113], v[146:149], v[214:217], v[110:113]
	v_mfma_i32_16x16x64_i8 v[106:109], v[160:163], v[214:217], v[106:109]
	v_mfma_i32_16x16x64_i8 v[94:97], v[146:149], v[222:225], v[94:97]
	v_mfma_i32_16x16x64_i8 v[90:93], v[160:163], v[222:225], v[90:93]
	v_mfma_i32_16x16x64_i8 v[78:81], v[146:149], v[230:233], v[78:81]
	v_mfma_i32_16x16x64_i8 v[74:77], v[160:163], v[230:233], v[74:77]
	v_mfma_i32_16x16x64_i8 v[128:131], v[156:159], v[198:201], v[128:131]
	v_mfma_i32_16x16x64_i8 v[124:127], v[164:167], v[198:201], v[124:127]
	v_mfma_i32_16x16x64_i8 v[110:113], v[156:159], v[218:221], v[110:113]
	v_mfma_i32_16x16x64_i8 v[106:109], v[164:167], v[218:221], v[106:109]
	v_mfma_i32_16x16x64_i8 v[94:97], v[156:159], v[226:229], v[94:97]
	v_mfma_i32_16x16x64_i8 v[90:93], v[164:167], v[226:229], v[90:93]
	v_mfma_i32_16x16x64_i8 v[78:81], v[156:159], v[234:237], v[78:81]
	v_mfma_i32_16x16x64_i8 v[74:77], v[164:167], v[234:237], v[74:77]
	s_setprio 0
	s_setprio 1
	v_mfma_i32_16x16x64_i8 v[120:123], v[168:171], v[194:197], v[120:123]
	v_mfma_i32_16x16x64_i8 v[116:119], v[176:179], v[194:197], v[116:119]
	v_mfma_i32_16x16x64_i8 v[102:105], v[168:171], v[214:217], v[102:105]
	v_mfma_i32_16x16x64_i8 v[98:101], v[176:179], v[214:217], v[98:101]
	v_mfma_i32_16x16x64_i8 v[86:89], v[168:171], v[222:225], v[86:89]
	v_mfma_i32_16x16x64_i8 v[82:85], v[176:179], v[222:225], v[82:85]
	v_mfma_i32_16x16x64_i8 v[70:73], v[168:171], v[230:233], v[70:73]
	v_mfma_i32_16x16x64_i8 v[66:69], v[176:179], v[230:233], v[66:69]
	v_mfma_i32_16x16x64_i8 v[120:123], v[172:175], v[198:201], v[120:123]
	v_mfma_i32_16x16x64_i8 v[116:119], v[182:185], v[198:201], v[116:119]
	v_mfma_i32_16x16x64_i8 v[102:105], v[172:175], v[218:221], v[102:105]
	v_mfma_i32_16x16x64_i8 v[98:101], v[182:185], v[218:221], v[98:101]
	v_mfma_i32_16x16x64_i8 v[86:89], v[172:175], v[226:229], v[86:89]
	v_mfma_i32_16x16x64_i8 v[82:85], v[182:185], v[226:229], v[82:85]
	v_mfma_i32_16x16x64_i8 v[70:73], v[172:175], v[234:237], v[70:73]
	v_mfma_i32_16x16x64_i8 v[66:69], v[182:185], v[234:237], v[66:69]
	s_setprio 0
	s_barrier
	s_add_i32 s16, s16, s28
	s_mov_b32 m0, s16
	ds_read_b128 v[194:197], v154 offset:16384
	ds_read_b128 v[198:201], v154 offset:17408
	ds_read_b128 v[214:217], v154 offset:18432
	ds_read_b128 v[218:221], v154 offset:19456
	ds_read_b128 v[222:225], v154 offset:20480
	ds_read_b128 v[226:229], v154 offset:21504
	ds_read_b128 v[230:233], v154 offset:22528
	ds_read_b128 v[234:237], v154 offset:23552
	global_load_lds_dwordx4 v136, s[10:11]
	s_add_i32 m0, s16, 0x2000
	s_add_u32 s16, s10, 0x4000
	s_addc_u32 s17, s11, 0
	s_add_i32 s55, s55, s28
	global_load_lds_dwordx4 v132, s[10:11]
	s_mov_b32 m0, s55
	s_nop 0
	global_load_lds_dwordx4 v136, s[16:17]
	s_add_i32 m0, s55, 0x2000
	s_nop 0
	global_load_lds_dwordx4 v132, s[16:17]
	s_add_u32 vcc_lo, s12, s64
	s_addc_u32 vcc_hi, s13, s65
	s_mov_b32 m0, s29
	s_nop 0
	global_load_lds_dwordx4 v138, s[12:13]
	s_mov_b32 m0, s34
	s_nop 0
	global_load_lds_dwordx4 v134, s[12:13]
	s_waitcnt vmcnt(8)
	s_waitcnt lgkmcnt(0)
	s_barrier
	s_setprio 1
	s_waitcnt lgkmcnt(0)
	v_mfma_i32_16x16x64_i8 v[62:65], v[146:149], v[194:197], v[62:65]
	v_mfma_i32_16x16x64_i8 v[58:61], v[160:163], v[194:197], v[58:61]
	v_mfma_i32_16x16x64_i8 v[46:49], v[146:149], v[214:217], v[46:49]
	v_mfma_i32_16x16x64_i8 v[42:45], v[160:163], v[214:217], v[42:45]
	v_mfma_i32_16x16x64_i8 v[30:33], v[146:149], v[222:225], v[30:33]
	v_mfma_i32_16x16x64_i8 v[26:29], v[160:163], v[222:225], v[26:29]
	v_mfma_i32_16x16x64_i8 v[14:17], v[146:149], v[230:233], v[14:17]
	v_mfma_i32_16x16x64_i8 v[10:13], v[160:163], v[230:233], v[10:13]
	v_mfma_i32_16x16x64_i8 v[62:65], v[156:159], v[198:201], v[62:65]
	v_mfma_i32_16x16x64_i8 v[58:61], v[164:167], v[198:201], v[58:61]
	v_mfma_i32_16x16x64_i8 v[46:49], v[156:159], v[218:221], v[46:49]
	v_mfma_i32_16x16x64_i8 v[42:45], v[164:167], v[218:221], v[42:45]
	v_mfma_i32_16x16x64_i8 v[30:33], v[156:159], v[226:229], v[30:33]
	v_mfma_i32_16x16x64_i8 v[26:29], v[164:167], v[226:229], v[26:29]
	v_mfma_i32_16x16x64_i8 v[14:17], v[156:159], v[234:237], v[14:17]
	v_mfma_i32_16x16x64_i8 v[10:13], v[164:167], v[234:237], v[10:13]
	s_setprio 0
	s_setprio 1
	v_mfma_i32_16x16x64_i8 v[54:57], v[168:171], v[194:197], v[54:57]
	v_mfma_i32_16x16x64_i8 v[50:53], v[176:179], v[194:197], v[50:53]
	v_mfma_i32_16x16x64_i8 v[38:41], v[168:171], v[214:217], v[38:41]
	v_mfma_i32_16x16x64_i8 v[34:37], v[176:179], v[214:217], v[34:37]
	v_mfma_i32_16x16x64_i8 v[22:25], v[168:171], v[222:225], v[22:25]
	v_mfma_i32_16x16x64_i8 v[18:21], v[176:179], v[222:225], v[18:21]
	v_mfma_i32_16x16x64_i8 v[6:9], v[168:171], v[230:233], v[6:9]
	v_mfma_i32_16x16x64_i8 v[2:5], v[176:179], v[230:233], v[2:5]
	v_mfma_i32_16x16x64_i8 v[54:57], v[172:175], v[198:201], v[54:57]
	v_mfma_i32_16x16x64_i8 v[50:53], v[182:185], v[198:201], v[50:53]
	v_mfma_i32_16x16x64_i8 v[38:41], v[172:175], v[218:221], v[38:41]
	v_mfma_i32_16x16x64_i8 v[34:37], v[182:185], v[218:221], v[34:37]
	v_mfma_i32_16x16x64_i8 v[22:25], v[172:175], v[226:229], v[22:25]
	v_mfma_i32_16x16x64_i8 v[18:21], v[182:185], v[226:229], v[18:21]
	v_mfma_i32_16x16x64_i8 v[6:9], v[172:175], v[234:237], v[6:9]
	v_mfma_i32_16x16x64_i8 v[2:5], v[182:185], v[234:237], v[2:5]
	s_setprio 0
	s_barrier
; #define PG8_STAGE(bufoff, gbase, voff) do { _Pragma("unroll") for (int _i = 0; _i < 2; ++_i) \
;         __builtin_amdgcn_global_load_lds((const unsigned*)((const char*)(gbase) + (voff)[_i]), (PG8_LAS unsigned*)(lds + (bufoff) + ldsw + _i * 8192), 16, 0, 0); } while (0)
; #define PG8_LDA(dst, b, h) do { _Pragma("unroll") for (int m = 0; m < 4; ++m) _Pragma("unroll") for (int k = 0; k < 2; ++k) dst[m][k] = *(const PG8_LAS frag_t*)(lds + PG8_SA(b, h) + aoff + m * 2048 + k * 1024); } while (0)
; #define PG8_LDB(dst, b, h) do { _Pragma("unroll") for (int n = 0; n < 2; ++n) _Pragma("unroll") for (int k = 0; k < 2; ++k) dst[n][k] = *(const PG8_LAS frag_t*)(lds + PG8_SB(b, h) + boff + n * 2048 + k * 1024); } while (0)
; #define PG8_MMA(ai, bj, At, Bt) do { __builtin_amdgcn_s_setprio(1); _Pragma("unroll") for (int m = 0; m < 4; ++m) _Pragma("unroll") for (int n = 0; n < 2; ++n) _Pragma("unroll") for (int k = 0; k < 2; ++k) \
;         acc[ai][bj][m][n] = MT<I8>::mma(Bt[n][k], At[m][k], acc[ai][bj][m][n]); __builtin_amdgcn_s_setprio(0); } while (0)
; #define PG8_WAIT_V(n) asm volatile("s_waitcnt vmcnt(" #n ")" ::: "memory")
; #define PG8_WAIT_L(n) asm volatile("s_waitcnt lgkmcnt(" #n ")" ::: "memory")
; #define PG8_BAR __builtin_amdgcn_s_barrier()
; #define PG8_SCHED __builtin_amdgcn_sched_barrier(0)
; template <class Epi, class Sched, bool ALIGN_EPI = false, bool SP2 = false, bool TILED_A = false, bool TILED_B = false, bool I8 = false>
; __device__ __forceinline__ void gemm_phase(PG8_LAS unsigned char* lds, const Gemm g, const Sched& S, const Epi& E) {
;     ...
;             PG8_LDB(B0, 1, 0); PG8_LDB(B1, 1, 1); PG8_SCHED; PG8_LDA(At, 1, 0); PG8_STAGE(PG8_SA(0, 1), a2 + hstepA, voffA);
;             PG8_WAIT_V(8); PG8_WAIT_L(0); PG8_BAR; PG8_MMA(0, 0, At, B0); PG8_MMA(0, 1, At, B1); PG8_BAR; PG8_SCHED;
;             PG8_LDA(At, 1, 1); PG8_STAGE(PG8_SB(1, 0), b3, voffB); PG8_STAGE(PG8_SB(1, 1), b3 + hstepB, voffB); PG8_STAGE(PG8_SA(1, 0), a3, voffA);
;             PG8_WAIT_V(8); PG8_WAIT_L(0); PG8_BAR; PG8_MMA(1, 0, At, B0); PG8_MMA(1, 1, At, B1); PG8_BAR; PG8_SCHED;
	s_add_i32 s16, 0, 0x18000
	v_add_u32_e32 v145, s16, v115
	s_add_i32 s17, 0, 0x1c000
	ds_read_b128 v[146:149], v145
	ds_read_b128 v[156:159], v145 offset:1024
	ds_read_b128 v[160:163], v145 offset:2048
	ds_read_b128 v[164:167], v145 offset:3072
	v_add_u32_e32 v145, s17, v115
	ds_read_b128 v[168:171], v145
	ds_read_b128 v[172:175], v145 offset:1024
	ds_read_b128 v[176:179], v145 offset:2048
	ds_read_b128 v[182:185], v145 offset:3072
	s_add_u32 s12, s12, 0x80000
	s_addc_u32 s13, s13, 0
	s_mov_b32 m0, s35
	ds_read_b128 v[194:197], v154 offset:32768
	ds_read_b128 v[198:201], v154 offset:33792
	ds_read_b128 v[214:217], v154 offset:34816
	ds_read_b128 v[218:221], v154 offset:35840
	ds_read_b128 v[222:225], v154 offset:36864
	ds_read_b128 v[226:229], v154 offset:37888
	ds_read_b128 v[230:233], v154 offset:38912
	ds_read_b128 v[234:237], v154 offset:39936
	global_load_lds_dwordx4 v138, s[12:13]
	s_mov_b32 m0, s36
	s_nop 0
	global_load_lds_dwordx4 v134, s[12:13]
	s_waitcnt vmcnt(8)
	s_waitcnt lgkmcnt(0)
	s_barrier
	s_setprio 1
	s_waitcnt lgkmcnt(0)
	v_mfma_i32_16x16x64_i8 v[128:131], v[146:149], v[194:197], v[128:131]
	v_mfma_i32_16x16x64_i8 v[124:127], v[160:163], v[194:197], v[124:127]
	v_mfma_i32_16x16x64_i8 v[110:113], v[146:149], v[214:217], v[110:113]
	v_mfma_i32_16x16x64_i8 v[106:109], v[160:163], v[214:217], v[106:109]
	v_mfma_i32_16x16x64_i8 v[94:97], v[146:149], v[222:225], v[94:97]
	v_mfma_i32_16x16x64_i8 v[90:93], v[160:163], v[222:225], v[90:93]
	v_mfma_i32_16x16x64_i8 v[78:81], v[146:149], v[230:233], v[78:81]
	v_mfma_i32_16x16x64_i8 v[74:77], v[160:163], v[230:233], v[74:77]
	v_mfma_i32_16x16x64_i8 v[128:131], v[156:159], v[198:201], v[128:131]
	v_mfma_i32_16x16x64_i8 v[124:127], v[164:167], v[198:201], v[124:127]
	v_mfma_i32_16x16x64_i8 v[110:113], v[156:159], v[218:221], v[110:113]
	v_mfma_i32_16x16x64_i8 v[106:109], v[164:167], v[218:221], v[106:109]
	v_mfma_i32_16x16x64_i8 v[94:97], v[156:159], v[226:229], v[94:97]
	v_mfma_i32_16x16x64_i8 v[90:93], v[164:167], v[226:229], v[90:93]
	v_mfma_i32_16x16x64_i8 v[78:81], v[156:159], v[234:237], v[78:81]
	v_mfma_i32_16x16x64_i8 v[74:77], v[164:167], v[234:237], v[74:77]
	s_setprio 0
	s_setprio 1
	v_mfma_i32_16x16x64_i8 v[120:123], v[168:171], v[194:197], v[120:123]
	v_mfma_i32_16x16x64_i8 v[116:119], v[176:179], v[194:197], v[116:119]
	v_mfma_i32_16x16x64_i8 v[102:105], v[168:171], v[214:217], v[102:105]
	v_mfma_i32_16x16x64_i8 v[98:101], v[176:179], v[214:217], v[98:101]
	v_mfma_i32_16x16x64_i8 v[86:89], v[168:171], v[222:225], v[86:89]
	v_mfma_i32_16x16x64_i8 v[82:85], v[176:179], v[222:225], v[82:85]
	v_mfma_i32_16x16x64_i8 v[70:73], v[168:171], v[230:233], v[70:73]
	v_mfma_i32_16x16x64_i8 v[66:69], v[176:179], v[230:233], v[66:69]
	v_mfma_i32_16x16x64_i8 v[120:123], v[172:175], v[198:201], v[120:123]
	v_mfma_i32_16x16x64_i8 v[116:119], v[182:185], v[198:201], v[116:119]
	v_mfma_i32_16x16x64_i8 v[102:105], v[172:175], v[218:221], v[102:105]
	v_mfma_i32_16x16x64_i8 v[98:101], v[182:185], v[218:221], v[98:101]
	v_mfma_i32_16x16x64_i8 v[86:89], v[172:175], v[226:229], v[86:89]
	v_mfma_i32_16x16x64_i8 v[82:85], v[182:185], v[226:229], v[82:85]
	v_mfma_i32_16x16x64_i8 v[70:73], v[172:175], v[234:237], v[70:73]
	v_mfma_i32_16x16x64_i8 v[66:69], v[182:185], v[234:237], v[66:69]
	s_setprio 0
	s_barrier
	s_add_u32 s12, s10, 0x8000
	s_addc_u32 s13, s11, 0
	s_add_i32 s16, s16, s28
	s_mov_b32 m0, s16
	ds_read_b128 v[194:197], v154 offset:49152
	ds_read_b128 v[198:201], v154 offset:50176
	ds_read_b128 v[214:217], v154 offset:51200
	ds_read_b128 v[218:221], v154 offset:52224
	ds_read_b128 v[222:225], v154 offset:53248
	ds_read_b128 v[226:229], v154 offset:54272
	ds_read_b128 v[230:233], v154 offset:55296
	ds_read_b128 v[234:237], v154 offset:56320
	global_load_lds_dwordx4 v136, s[12:13]
	s_add_i32 m0, s16, 0x2000
	s_add_u32 s10, s10, 0xc000
	s_addc_u32 s11, s11, 0
	global_load_lds_dwordx4 v132, s[12:13]
	s_add_i32 s12, s17, s28
	s_mov_b32 m0, s12
	s_nop 0
	global_load_lds_dwordx4 v136, s[10:11]
	s_add_i32 m0, s12, 0x2000
	s_nop 0
	global_load_lds_dwordx4 v132, s[10:11]
	s_mov_b32 m0, s66
	s_nop 0
	global_load_lds_dwordx4 v138, vcc
	s_mov_b32 m0, s67
	s_nop 0
	global_load_lds_dwordx4 v134, vcc
	s_waitcnt vmcnt(8)
	s_waitcnt lgkmcnt(0)
	s_barrier
	s_setprio 1
	s_waitcnt lgkmcnt(0)
	v_mfma_i32_16x16x64_i8 v[62:65], v[146:149], v[194:197], v[62:65]
	v_mfma_i32_16x16x64_i8 v[58:61], v[160:163], v[194:197], v[58:61]
	v_mfma_i32_16x16x64_i8 v[46:49], v[146:149], v[214:217], v[46:49]
	v_mfma_i32_16x16x64_i8 v[42:45], v[160:163], v[214:217], v[42:45]
	v_mfma_i32_16x16x64_i8 v[30:33], v[146:149], v[222:225], v[30:33]
	v_mfma_i32_16x16x64_i8 v[26:29], v[160:163], v[222:225], v[26:29]
	v_mfma_i32_16x16x64_i8 v[14:17], v[146:149], v[230:233], v[14:17]
	v_mfma_i32_16x16x64_i8 v[10:13], v[160:163], v[230:233], v[10:13]
	v_mfma_i32_16x16x64_i8 v[62:65], v[156:159], v[198:201], v[62:65]
	v_mfma_i32_16x16x64_i8 v[58:61], v[164:167], v[198:201], v[58:61]
	v_mfma_i32_16x16x64_i8 v[46:49], v[156:159], v[218:221], v[46:49]
	v_mfma_i32_16x16x64_i8 v[42:45], v[164:167], v[218:221], v[42:45]
	v_mfma_i32_16x16x64_i8 v[30:33], v[156:159], v[226:229], v[30:33]
	v_mfma_i32_16x16x64_i8 v[26:29], v[164:167], v[226:229], v[26:29]
	v_mfma_i32_16x16x64_i8 v[14:17], v[156:159], v[234:237], v[14:17]
	v_mfma_i32_16x16x64_i8 v[10:13], v[164:167], v[234:237], v[10:13]
	s_setprio 0
	s_setprio 1
	v_mfma_i32_16x16x64_i8 v[54:57], v[168:171], v[194:197], v[54:57]
	v_mfma_i32_16x16x64_i8 v[50:53], v[176:179], v[194:197], v[50:53]
	v_mfma_i32_16x16x64_i8 v[38:41], v[168:171], v[214:217], v[38:41]
	v_mfma_i32_16x16x64_i8 v[34:37], v[176:179], v[214:217], v[34:37]
	v_mfma_i32_16x16x64_i8 v[22:25], v[168:171], v[222:225], v[22:25]
	v_mfma_i32_16x16x64_i8 v[18:21], v[176:179], v[222:225], v[18:21]
	v_mfma_i32_16x16x64_i8 v[6:9], v[168:171], v[230:233], v[6:9]
	v_mfma_i32_16x16x64_i8 v[2:5], v[176:179], v[230:233], v[2:5]
	v_mfma_i32_16x16x64_i8 v[54:57], v[172:175], v[198:201], v[54:57]
	v_mfma_i32_16x16x64_i8 v[50:53], v[182:185], v[198:201], v[50:53]
	v_mfma_i32_16x16x64_i8 v[38:41], v[172:175], v[218:221], v[38:41]
	v_mfma_i32_16x16x64_i8 v[34:37], v[182:185], v[218:221], v[34:37]
	v_mfma_i32_16x16x64_i8 v[22:25], v[172:175], v[226:229], v[22:25]
	v_mfma_i32_16x16x64_i8 v[18:21], v[182:185], v[226:229], v[18:21]
	v_mfma_i32_16x16x64_i8 v[6:9], v[172:175], v[234:237], v[6:9]
	v_mfma_i32_16x16x64_i8 v[2:5], v[182:185], v[234:237], v[2:5]
	s_setprio 0
	s_barrier
	s_add_i32 s53, s53, 2
	s_add_u32 s24, s24, 0x10000
	s_addc_u32 s48, s48, 0
	s_add_u32 s6, s6, 0x100
	s_addc_u32 s7, s7, 0
	s_cmp_gt_u32 s53, 29
	s_cbranch_scc0 .LBB0_718
	s_and_b64 vcc, exec, s[50:51]
	s_cbranch_vccz .LBB0_721
	s_barrier

; #define PG8_STAGE(bufoff, gbase, voff) do { _Pragma("unroll") for (int _i = 0; _i < 2; ++_i) \
;         __builtin_amdgcn_global_load_lds((const unsigned*)((const char*)(gbase) + (voff)[_i]), (PG8_LAS unsigned*)(lds + (bufoff) + ldsw + _i * 8192), 16, 0, 0); } while (0)
; #define PG8_LDA(dst, b, h) do { _Pragma("unroll") for (int m = 0; m < 4; ++m) _Pragma("unroll") for (int k = 0; k < 2; ++k) dst[m][k] = *(const PG8_LAS frag_t*)(lds + PG8_SA(b, h) + aoff + m * 2048 + k * 1024); } while (0)
; #define PG8_LDB(dst, b, h) do { _Pragma("unroll") for (int n = 0; n < 2; ++n) _Pragma("unroll") for (int k = 0; k < 2; ++k) dst[n][k] = *(const PG8_LAS frag_t*)(lds + PG8_SB(b, h) + boff + n * 2048 + k * 1024); } while (0)
; #define PG8_MMA(ai, bj, At, Bt) do { __builtin_amdgcn_s_setprio(1); _Pragma("unroll") for (int m = 0; m < 4; ++m) _Pragma("unroll") for (int n = 0; n < 2; ++n) _Pragma("unroll") for (int k = 0; k < 2; ++k) \
;         acc[ai][bj][m][n] = MT<I8>::mma(Bt[n][k], At[m][k], acc[ai][bj][m][n]); __builtin_amdgcn_s_setprio(0); } while (0)
; #define PG8_WAIT_V(n) asm volatile("s_waitcnt vmcnt(" #n ")" ::: "memory")
; #define PG8_WAIT_L(n) asm volatile("s_waitcnt lgkmcnt(" #n ")" ::: "memory")
; #define PG8_BAR __builtin_amdgcn_s_barrier()
; #define PG8_SCHED __builtin_amdgcn_sched_barrier(0)
; template <class Epi, class Sched, bool ALIGN_EPI = false, bool SP2 = false, bool TILED_A = false, bool TILED_B = false, bool I8 = false>
; __device__ __forceinline__ void gemm_phase(PG8_LAS unsigned char* lds, const Gemm g, const Sched& S, const Epi& E) {
;     ...
;             PG8_LDB(B0, 0, 0); PG8_LDB(B1, 0, 1); PG8_SCHED; PG8_LDA(At, 0, 0); PG8_STAGE(PG8_SA(1, 1), a1 + hstepA, voffA);
;             PG8_WAIT_V(8); PG8_WAIT_L(0); PG8_BAR; PG8_MMA(0, 0, At, B0); PG8_MMA(0, 1, At, B1); PG8_BAR; PG8_SCHED;
;             PG8_LDA(At, 0, 1); PG8_STAGE(PG8_SB(0, 0), b2, voffB); PG8_STAGE(PG8_SB(0, 1), b2 + hstepB, voffB); PG8_STAGE(PG8_SA(0, 0), a2, voffA);
;             PG8_WAIT_V(8); PG8_WAIT_L(0); PG8_BAR; PG8_MMA(1, 0, At, B0); PG8_MMA(1, 1, At, B1); PG8_BAR; PG8_SCHED;
.LBB0_870:
	s_add_u32 s10, s8, 0x4000
	s_addc_u32 s11, s9, 0
	s_cmpk_eq_i32 s57, 0x7c
	s_cselect_b32 s34, s7, s10
	s_cselect_b32 s35, s3, s11
	s_cselect_b32 s12, s23, s24
	s_cselect_b32 s13, s22, s55
	s_add_u32 s10, s34, 0x8000
	s_addc_u32 s11, s35, 0
	s_add_i32 s16, 0, 0x10000
	s_add_i32 s68, 0, 0x14000
	v_add_u32_e32 v158, s16, v115
	v_add_u32_e32 v174, s68, v115
	ds_read_b128 v[144:147], v158
	ds_read_b128 v[148:151], v158 offset:1024
	ds_read_b128 v[154:157], v158 offset:2048
	ds_read_b128 v[158:161], v158 offset:3072
	ds_read_b128 v[162:165], v174
	ds_read_b128 v[166:169], v174 offset:1024
	ds_read_b128 v[170:173], v174 offset:2048
	ds_read_b128 v[174:177], v174 offset:3072
	s_add_i32 m0, s36, 0xc000
	ds_read_b128 v[182:185], v153
	ds_read_b128 v[194:197], v153 offset:1024
	ds_read_b128 v[198:201], v153 offset:2048
	ds_read_b128 v[214:217], v153 offset:3072
	ds_read_b128 v[218:221], v153 offset:4096
	ds_read_b128 v[222:225], v153 offset:5120
	ds_read_b128 v[226:229], v153 offset:6144
	ds_read_b128 v[230:233], v153 offset:7168
	global_load_lds_dwordx4 v140, s[8:9]
	s_add_i32 m0, s36, 0xe000
	s_nop 0
	global_load_lds_dwordx4 v142, s[8:9]
	s_waitcnt vmcnt(8)
	s_waitcnt lgkmcnt(0)
	s_barrier
	s_setprio 1
	s_waitcnt lgkmcnt(0)
	v_mfma_i32_16x16x64_i8 v[128:131], v[144:147], v[182:185], v[128:131]
	v_mfma_i32_16x16x64_i8 v[124:127], v[154:157], v[182:185], v[124:127]
	v_mfma_i32_16x16x64_i8 v[120:123], v[144:147], v[198:201], v[120:123]
	v_mfma_i32_16x16x64_i8 v[116:119], v[154:157], v[198:201], v[116:119]
	v_mfma_i32_16x16x64_i8 v[110:113], v[144:147], v[218:221], v[110:113]
	v_mfma_i32_16x16x64_i8 v[106:109], v[154:157], v[218:221], v[106:109]
	v_mfma_i32_16x16x64_i8 v[102:105], v[144:147], v[226:229], v[102:105]
	v_mfma_i32_16x16x64_i8 v[98:101], v[154:157], v[226:229], v[98:101]
	v_mfma_i32_16x16x64_i8 v[128:131], v[148:151], v[194:197], v[128:131]
	v_mfma_i32_16x16x64_i8 v[124:127], v[158:161], v[194:197], v[124:127]
	v_mfma_i32_16x16x64_i8 v[120:123], v[148:151], v[214:217], v[120:123]
	v_mfma_i32_16x16x64_i8 v[116:119], v[158:161], v[214:217], v[116:119]
	v_mfma_i32_16x16x64_i8 v[110:113], v[148:151], v[222:225], v[110:113]
	v_mfma_i32_16x16x64_i8 v[106:109], v[158:161], v[222:225], v[106:109]
	v_mfma_i32_16x16x64_i8 v[102:105], v[148:151], v[230:233], v[102:105]
	v_mfma_i32_16x16x64_i8 v[98:101], v[158:161], v[230:233], v[98:101]
	s_setprio 0
	s_setprio 1
	v_mfma_i32_16x16x64_i8 v[62:65], v[162:165], v[182:185], v[62:65]
	v_mfma_i32_16x16x64_i8 v[58:61], v[170:173], v[182:185], v[58:61]
	v_mfma_i32_16x16x64_i8 v[54:57], v[162:165], v[198:201], v[54:57]
	v_mfma_i32_16x16x64_i8 v[50:53], v[170:173], v[198:201], v[50:53]
	v_mfma_i32_16x16x64_i8 v[46:49], v[162:165], v[218:221], v[46:49]
	v_mfma_i32_16x16x64_i8 v[42:45], v[170:173], v[218:221], v[42:45]
	v_mfma_i32_16x16x64_i8 v[38:41], v[162:165], v[226:229], v[38:41]
	v_mfma_i32_16x16x64_i8 v[34:37], v[170:173], v[226:229], v[34:37]
	v_mfma_i32_16x16x64_i8 v[62:65], v[166:169], v[194:197], v[62:65]
	v_mfma_i32_16x16x64_i8 v[58:61], v[174:177], v[194:197], v[58:61]
	v_mfma_i32_16x16x64_i8 v[54:57], v[166:169], v[214:217], v[54:57]
	v_mfma_i32_16x16x64_i8 v[50:53], v[174:177], v[214:217], v[50:53]
	v_mfma_i32_16x16x64_i8 v[46:49], v[166:169], v[222:225], v[46:49]
	v_mfma_i32_16x16x64_i8 v[42:45], v[174:177], v[222:225], v[42:45]
	v_mfma_i32_16x16x64_i8 v[38:41], v[166:169], v[230:233], v[38:41]
	v_mfma_i32_16x16x64_i8 v[34:37], v[174:177], v[230:233], v[34:37]
	s_setprio 0
	s_barrier
	s_add_i32 s16, s16, s27
	s_mov_b32 m0, s16
	ds_read_b128 v[182:185], v153 offset:16384
	ds_read_b128 v[194:197], v153 offset:17408
	ds_read_b128 v[198:201], v153 offset:18432
	ds_read_b128 v[214:217], v153 offset:19456
	ds_read_b128 v[218:221], v153 offset:20480
	ds_read_b128 v[222:225], v153 offset:21504
	ds_read_b128 v[226:229], v153 offset:22528
	ds_read_b128 v[230:233], v153 offset:23552
	global_load_lds_dwordx4 v134, s[12:13]
	s_add_i32 m0, s16, 0x2000
	s_add_u32 s16, s12, 0x4000
	s_addc_u32 s17, s13, 0
	s_add_i32 s68, s68, s27
	global_load_lds_dwordx4 v138, s[12:13]
	s_mov_b32 m0, s68
	s_nop 0
	global_load_lds_dwordx4 v134, s[16:17]
	s_add_i32 m0, s68, 0x2000
	s_nop 0
	global_load_lds_dwordx4 v138, s[16:17]
	s_mov_b32 m0, s36
	s_nop 0
	global_load_lds_dwordx4 v132, s[34:35]
	s_mov_b32 m0, s37
	s_nop 0
	global_load_lds_dwordx4 v136, s[34:35]
	s_waitcnt vmcnt(8)
	s_waitcnt lgkmcnt(0)
	s_barrier
	s_setprio 1
	s_waitcnt lgkmcnt(0)
	v_mfma_i32_16x16x64_i8 v[94:97], v[144:147], v[182:185], v[94:97]
	v_mfma_i32_16x16x64_i8 v[90:93], v[154:157], v[182:185], v[90:93]
	v_mfma_i32_16x16x64_i8 v[86:89], v[144:147], v[198:201], v[86:89]
	v_mfma_i32_16x16x64_i8 v[82:85], v[154:157], v[198:201], v[82:85]
	v_mfma_i32_16x16x64_i8 v[78:81], v[144:147], v[218:221], v[78:81]
	v_mfma_i32_16x16x64_i8 v[74:77], v[154:157], v[218:221], v[74:77]
	v_mfma_i32_16x16x64_i8 v[70:73], v[144:147], v[226:229], v[70:73]
	v_mfma_i32_16x16x64_i8 v[66:69], v[154:157], v[226:229], v[66:69]
	v_mfma_i32_16x16x64_i8 v[94:97], v[148:151], v[194:197], v[94:97]
	v_mfma_i32_16x16x64_i8 v[90:93], v[158:161], v[194:197], v[90:93]
	v_mfma_i32_16x16x64_i8 v[86:89], v[148:151], v[214:217], v[86:89]
	v_mfma_i32_16x16x64_i8 v[82:85], v[158:161], v[214:217], v[82:85]
	v_mfma_i32_16x16x64_i8 v[78:81], v[148:151], v[222:225], v[78:81]
	v_mfma_i32_16x16x64_i8 v[74:77], v[158:161], v[222:225], v[74:77]
	v_mfma_i32_16x16x64_i8 v[70:73], v[148:151], v[230:233], v[70:73]
	v_mfma_i32_16x16x64_i8 v[66:69], v[158:161], v[230:233], v[66:69]
	s_setprio 0
	s_setprio 1
	v_mfma_i32_16x16x64_i8 v[30:33], v[162:165], v[182:185], v[30:33]
	v_mfma_i32_16x16x64_i8 v[26:29], v[170:173], v[182:185], v[26:29]
	v_mfma_i32_16x16x64_i8 v[22:25], v[162:165], v[198:201], v[22:25]
	v_mfma_i32_16x16x64_i8 v[18:21], v[170:173], v[198:201], v[18:21]
	v_mfma_i32_16x16x64_i8 v[14:17], v[162:165], v[218:221], v[14:17]
	v_mfma_i32_16x16x64_i8 v[10:13], v[170:173], v[218:221], v[10:13]
	v_mfma_i32_16x16x64_i8 v[6:9], v[162:165], v[226:229], v[6:9]
	v_mfma_i32_16x16x64_i8 v[2:5], v[170:173], v[226:229], v[2:5]
	v_mfma_i32_16x16x64_i8 v[30:33], v[166:169], v[194:197], v[30:33]
	v_mfma_i32_16x16x64_i8 v[26:29], v[174:177], v[194:197], v[26:29]
	v_mfma_i32_16x16x64_i8 v[22:25], v[166:169], v[214:217], v[22:25]
	v_mfma_i32_16x16x64_i8 v[18:21], v[174:177], v[214:217], v[18:21]
	v_mfma_i32_16x16x64_i8 v[14:17], v[166:169], v[222:225], v[14:17]
	v_mfma_i32_16x16x64_i8 v[10:13], v[174:177], v[222:225], v[10:13]
	v_mfma_i32_16x16x64_i8 v[6:9], v[166:169], v[230:233], v[6:9]
	v_mfma_i32_16x16x64_i8 v[2:5], v[174:177], v[230:233], v[2:5]
	s_setprio 0
	s_barrier
; #define PG8_STAGE(bufoff, gbase, voff) do { _Pragma("unroll") for (int _i = 0; _i < 2; ++_i) \
;         __builtin_amdgcn_global_load_lds((const unsigned*)((const char*)(gbase) + (voff)[_i]), (PG8_LAS unsigned*)(lds + (bufoff) + ldsw + _i * 8192), 16, 0, 0); } while (0)
; #define PG8_LDA(dst, b, h) do { _Pragma("unroll") for (int m = 0; m < 4; ++m) _Pragma("unroll") for (int k = 0; k < 2; ++k) dst[m][k] = *(const PG8_LAS frag_t*)(lds + PG8_SA(b, h) + aoff + m * 2048 + k * 1024); } while (0)
; #define PG8_LDB(dst, b, h) do { _Pragma("unroll") for (int n = 0; n < 2; ++n) _Pragma("unroll") for (int k = 0; k < 2; ++k) dst[n][k] = *(const PG8_LAS frag_t*)(lds + PG8_SB(b, h) + boff + n * 2048 + k * 1024); } while (0)
; #define PG8_MMA(ai, bj, At, Bt) do { __builtin_amdgcn_s_setprio(1); _Pragma("unroll") for (int m = 0; m < 4; ++m) _Pragma("unroll") for (int n = 0; n < 2; ++n) _Pragma("unroll") for (int k = 0; k < 2; ++k) \
;         acc[ai][bj][m][n] = MT<I8>::mma(Bt[n][k], At[m][k], acc[ai][bj][m][n]); __builtin_amdgcn_s_setprio(0); } while (0)
; #define PG8_WAIT_V(n) asm volatile("s_waitcnt vmcnt(" #n ")" ::: "memory")
; #define PG8_WAIT_L(n) asm volatile("s_waitcnt lgkmcnt(" #n ")" ::: "memory")
; #define PG8_BAR __builtin_amdgcn_s_barrier()
; #define PG8_SCHED __builtin_amdgcn_sched_barrier(0)
; template <class Epi, class Sched, bool ALIGN_EPI = false, bool SP2 = false, bool TILED_A = false, bool TILED_B = false, bool I8 = false>
; __device__ __forceinline__ void gemm_phase(PG8_LAS unsigned char* lds, const Gemm g, const Sched& S, const Epi& E) {
;     ...
;             PG8_LDB(B0, 1, 0); PG8_LDB(B1, 1, 1); PG8_SCHED; PG8_LDA(At, 1, 0); PG8_STAGE(PG8_SA(0, 1), a2 + hstepA, voffA);
;             PG8_WAIT_V(8); PG8_WAIT_L(0); PG8_BAR; PG8_MMA(0, 0, At, B0); PG8_MMA(0, 1, At, B1); PG8_BAR; PG8_SCHED;
;             PG8_LDA(At, 1, 1); PG8_STAGE(PG8_SB(1, 0), b3, voffB); PG8_STAGE(PG8_SB(1, 1), b3 + hstepB, voffB); PG8_STAGE(PG8_SA(1, 0), a3, voffA);
;             PG8_WAIT_V(8); PG8_WAIT_L(0); PG8_BAR; PG8_MMA(1, 0, At, B0); PG8_MMA(1, 1, At, B1); PG8_BAR; PG8_SCHED;
	s_add_i32 s68, 0, 0x18000
	s_add_i32 s69, 0, 0x1c000
	v_add_u32_e32 v158, s68, v115
	v_add_u32_e32 v174, s69, v115
	ds_read_b128 v[144:147], v158
	ds_read_b128 v[148:151], v158 offset:1024
	ds_read_b128 v[154:157], v158 offset:2048
	ds_read_b128 v[158:161], v158 offset:3072
	ds_read_b128 v[162:165], v174
	ds_read_b128 v[166:169], v174 offset:1024
	ds_read_b128 v[170:173], v174 offset:2048
	ds_read_b128 v[174:177], v174 offset:3072
	s_add_u32 s16, s34, 0x4000
	s_addc_u32 s17, s35, 0
	s_mov_b32 m0, s63
	ds_read_b128 v[182:185], v153 offset:32768
	ds_read_b128 v[194:197], v153 offset:33792
	ds_read_b128 v[198:201], v153 offset:34816
	ds_read_b128 v[214:217], v153 offset:35840
	ds_read_b128 v[218:221], v153 offset:36864
	ds_read_b128 v[222:225], v153 offset:37888
	ds_read_b128 v[226:229], v153 offset:38912
	ds_read_b128 v[230:233], v153 offset:39936
	global_load_lds_dwordx4 v132, s[16:17]
	s_mov_b32 m0, s66
	s_nop 0
	global_load_lds_dwordx4 v136, s[16:17]
	s_waitcnt vmcnt(8)
	s_waitcnt lgkmcnt(0)
	s_barrier
	s_setprio 1
	s_waitcnt lgkmcnt(0)
	v_mfma_i32_16x16x64_i8 v[128:131], v[144:147], v[182:185], v[128:131]
	v_mfma_i32_16x16x64_i8 v[124:127], v[154:157], v[182:185], v[124:127]
	v_mfma_i32_16x16x64_i8 v[120:123], v[144:147], v[198:201], v[120:123]
	v_mfma_i32_16x16x64_i8 v[116:119], v[154:157], v[198:201], v[116:119]
	v_mfma_i32_16x16x64_i8 v[110:113], v[144:147], v[218:221], v[110:113]
	v_mfma_i32_16x16x64_i8 v[106:109], v[154:157], v[218:221], v[106:109]
	v_mfma_i32_16x16x64_i8 v[102:105], v[144:147], v[226:229], v[102:105]
	v_mfma_i32_16x16x64_i8 v[98:101], v[154:157], v[226:229], v[98:101]
	v_mfma_i32_16x16x64_i8 v[128:131], v[148:151], v[194:197], v[128:131]
	v_mfma_i32_16x16x64_i8 v[124:127], v[158:161], v[194:197], v[124:127]
	v_mfma_i32_16x16x64_i8 v[120:123], v[148:151], v[214:217], v[120:123]
	v_mfma_i32_16x16x64_i8 v[116:119], v[158:161], v[214:217], v[116:119]
	v_mfma_i32_16x16x64_i8 v[110:113], v[148:151], v[222:225], v[110:113]
	v_mfma_i32_16x16x64_i8 v[106:109], v[158:161], v[222:225], v[106:109]
	v_mfma_i32_16x16x64_i8 v[102:105], v[148:151], v[230:233], v[102:105]
	v_mfma_i32_16x16x64_i8 v[98:101], v[158:161], v[230:233], v[98:101]
	s_setprio 0
	s_setprio 1
	v_mfma_i32_16x16x64_i8 v[62:65], v[162:165], v[182:185], v[62:65]
	v_mfma_i32_16x16x64_i8 v[58:61], v[170:173], v[182:185], v[58:61]
	v_mfma_i32_16x16x64_i8 v[54:57], v[162:165], v[198:201], v[54:57]
	v_mfma_i32_16x16x64_i8 v[50:53], v[170:173], v[198:201], v[50:53]
	v_mfma_i32_16x16x64_i8 v[46:49], v[162:165], v[218:221], v[46:49]
	v_mfma_i32_16x16x64_i8 v[42:45], v[170:173], v[218:221], v[42:45]
	v_mfma_i32_16x16x64_i8 v[38:41], v[162:165], v[226:229], v[38:41]
	v_mfma_i32_16x16x64_i8 v[34:37], v[170:173], v[226:229], v[34:37]
	v_mfma_i32_16x16x64_i8 v[62:65], v[166:169], v[194:197], v[62:65]
	v_mfma_i32_16x16x64_i8 v[58:61], v[174:177], v[194:197], v[58:61]
	v_mfma_i32_16x16x64_i8 v[54:57], v[166:169], v[214:217], v[54:57]
	v_mfma_i32_16x16x64_i8 v[50:53], v[174:177], v[214:217], v[50:53]
	v_mfma_i32_16x16x64_i8 v[46:49], v[166:169], v[222:225], v[46:49]
	v_mfma_i32_16x16x64_i8 v[42:45], v[174:177], v[222:225], v[42:45]
	v_mfma_i32_16x16x64_i8 v[38:41], v[166:169], v[230:233], v[38:41]
	v_mfma_i32_16x16x64_i8 v[34:37], v[174:177], v[230:233], v[34:37]
	s_setprio 0
	s_barrier
	s_add_u32 s16, s12, 0x8000
	s_addc_u32 s17, s13, 0
	s_add_i32 s34, s68, s27
	s_mov_b32 m0, s34
	ds_read_b128 v[182:185], v153 offset:49152
	ds_read_b128 v[194:197], v153 offset:50176
	ds_read_b128 v[198:201], v153 offset:51200
	ds_read_b128 v[214:217], v153 offset:52224
	ds_read_b128 v[218:221], v153 offset:53248
	ds_read_b128 v[222:225], v153 offset:54272
	ds_read_b128 v[226:229], v153 offset:55296
	ds_read_b128 v[230:233], v153 offset:56320
	global_load_lds_dwordx4 v134, s[16:17]
	s_add_i32 m0, s34, 0x2000
	s_add_u32 s12, s12, 0xc000
	s_addc_u32 s13, s13, 0
	global_load_lds_dwordx4 v138, s[16:17]
	s_add_i32 s16, s69, s27
	s_mov_b32 m0, s16
	s_nop 0
	global_load_lds_dwordx4 v134, s[12:13]
	s_add_i32 m0, s16, 0x2000
	s_nop 0
	global_load_lds_dwordx4 v138, s[12:13]
	s_mov_b32 m0, s48
	s_nop 0
	global_load_lds_dwordx4 v132, s[10:11]
	s_mov_b32 m0, s67
	s_nop 0
	global_load_lds_dwordx4 v136, s[10:11]
	s_waitcnt vmcnt(8)
	s_waitcnt lgkmcnt(0)
	s_barrier
	s_setprio 1
	s_waitcnt lgkmcnt(0)
	v_mfma_i32_16x16x64_i8 v[94:97], v[144:147], v[182:185], v[94:97]
	v_mfma_i32_16x16x64_i8 v[90:93], v[154:157], v[182:185], v[90:93]
	v_mfma_i32_16x16x64_i8 v[86:89], v[144:147], v[198:201], v[86:89]
	v_mfma_i32_16x16x64_i8 v[82:85], v[154:157], v[198:201], v[82:85]
	v_mfma_i32_16x16x64_i8 v[78:81], v[144:147], v[218:221], v[78:81]
	v_mfma_i32_16x16x64_i8 v[74:77], v[154:157], v[218:221], v[74:77]
	v_mfma_i32_16x16x64_i8 v[70:73], v[144:147], v[226:229], v[70:73]
	v_mfma_i32_16x16x64_i8 v[66:69], v[154:157], v[226:229], v[66:69]
	v_mfma_i32_16x16x64_i8 v[94:97], v[148:151], v[194:197], v[94:97]
	v_mfma_i32_16x16x64_i8 v[90:93], v[158:161], v[194:197], v[90:93]
	v_mfma_i32_16x16x64_i8 v[86:89], v[148:151], v[214:217], v[86:89]
	v_mfma_i32_16x16x64_i8 v[82:85], v[158:161], v[214:217], v[82:85]
	v_mfma_i32_16x16x64_i8 v[78:81], v[148:151], v[222:225], v[78:81]
	v_mfma_i32_16x16x64_i8 v[74:77], v[158:161], v[222:225], v[74:77]
	v_mfma_i32_16x16x64_i8 v[70:73], v[148:151], v[230:233], v[70:73]
	v_mfma_i32_16x16x64_i8 v[66:69], v[158:161], v[230:233], v[66:69]
	s_setprio 0
	s_setprio 1
	v_mfma_i32_16x16x64_i8 v[30:33], v[162:165], v[182:185], v[30:33]
	v_mfma_i32_16x16x64_i8 v[26:29], v[170:173], v[182:185], v[26:29]
	v_mfma_i32_16x16x64_i8 v[22:25], v[162:165], v[198:201], v[22:25]
	v_mfma_i32_16x16x64_i8 v[18:21], v[170:173], v[198:201], v[18:21]
	v_mfma_i32_16x16x64_i8 v[14:17], v[162:165], v[218:221], v[14:17]
	v_mfma_i32_16x16x64_i8 v[10:13], v[170:173], v[218:221], v[10:13]
	v_mfma_i32_16x16x64_i8 v[6:9], v[162:165], v[226:229], v[6:9]
	v_mfma_i32_16x16x64_i8 v[2:5], v[170:173], v[226:229], v[2:5]
	v_mfma_i32_16x16x64_i8 v[30:33], v[166:169], v[194:197], v[30:33]
	v_mfma_i32_16x16x64_i8 v[26:29], v[174:177], v[194:197], v[26:29]
	v_mfma_i32_16x16x64_i8 v[22:25], v[166:169], v[214:217], v[22:25]
	v_mfma_i32_16x16x64_i8 v[18:21], v[174:177], v[214:217], v[18:21]
	v_mfma_i32_16x16x64_i8 v[14:17], v[166:169], v[222:225], v[14:17]
	v_mfma_i32_16x16x64_i8 v[10:13], v[174:177], v[222:225], v[10:13]
	v_mfma_i32_16x16x64_i8 v[6:9], v[166:169], v[230:233], v[6:9]
	v_mfma_i32_16x16x64_i8 v[2:5], v[174:177], v[230:233], v[2:5]
	s_setprio 0
	s_barrier
	s_add_i32 s57, s57, 2
	s_add_u32 s8, s8, 0x10000
	s_addc_u32 s9, s9, 0
	s_add_u32 s24, s24, 0x10000
	s_addc_u32 s55, s55, 0
	s_cmpk_gt_u32 s57, 0x7d
	s_cbranch_scc0 .LBB0_870
	s_and_b64 vcc, exec, s[52:53]
	s_cbranch_vccz .LBB0_873
	s_barrier
